# MoBA gating dot-product loops fully unrolled with all 16 query-row global loads of each loop issued up front and counted vmcnt waits
# baseline (speedup 1.0000x reference)
.LBB0_890:
	global_load_dwordx4 v[112:115], v[2:3], off offset:16
	global_load_dwordx4 v[116:119], v[2:3], off
	global_load_dwordx4 v[120:123], v[2:3], off offset:-16
	global_load_dwordx4 v[124:127], v[2:3], off offset:-32
	global_load_dwordx4 v[128:131], v[2:3], off offset:80
	global_load_dwordx4 v[132:135], v[2:3], off offset:64
	global_load_dwordx4 v[136:139], v[2:3], off offset:48
	global_load_dwordx4 v[140:143], v[2:3], off offset:32
	global_load_dwordx4 v[144:147], v[2:3], off offset:144
	global_load_dwordx4 v[194:197], v[2:3], off offset:128
	global_load_dwordx4 v[198:201], v[2:3], off offset:112
	global_load_dwordx4 v[202:205], v[2:3], off offset:96
	global_load_dwordx4 v[206:209], v[2:3], off offset:208
	global_load_dwordx4 v[210:213], v[2:3], off offset:192
	global_load_dwordx4 v[214:217], v[2:3], off offset:176
	global_load_dwordx4 v[218:221], v[2:3], off offset:160
	v_add_u32_e32 v13, s5, v8
	v_add_u32_e32 v30, 0x11800, v13
	v_add_u32_e32 v34, 0x12000, v13
	ds_read_b128 v[30:33], v30
	ds_read_b128 v[34:37], v34
	v_add_u32_e32 v40, 0x11810, v13
	v_add_u32_e32 v41, 0x12010, v13
	s_addk_i32 s5, 0x80
	s_waitcnt lgkmcnt(1)
	v_mov_b32_e32 v39, v31
	s_waitcnt lgkmcnt(0)
	v_pk_mov_b32 v[30:31], v[34:35], v[30:31] op_sel:[1,0]
	v_mov_b32_e32 v38, v34
	v_lshl_add_u64 v[2:3], v[2:3], 0, 64
	s_cmpk_eq_i32 s5, 0x200
	s_waitcnt vmcnt(12)
	v_and_b32_e32 v7, 0xffff0000, v124
	v_lshlrev_b32_e32 v6, 16, v124
	v_pk_mul_f32 v[30:31], v[30:31], v[6:7] op_sel:[0,1] op_sel_hi:[1,0]
	v_mov_b32_e32 v124, v36
	v_pk_fma_f32 v[6:7], v[38:39], v[6:7], v[30:31]
	v_pk_mov_b32 v[30:31], v[36:37], v[32:33] op_sel:[1,0]
	v_pk_add_f32 v[4:5], v[4:5], v[6:7]
	v_and_b32_e32 v7, 0xffff0000, v125
	v_lshlrev_b32_e32 v6, 16, v125
	v_mov_b32_e32 v125, v33
	v_pk_mul_f32 v[30:31], v[30:31], v[6:7] op_sel:[0,1] op_sel_hi:[1,0]
	v_and_b32_e32 v35, 0xffff0000, v126
	v_pk_fma_f32 v[6:7], v[124:125], v[6:7], v[30:31]
	v_lshlrev_b32_e32 v34, 16, v126
	v_pk_add_f32 v[124:125], v[4:5], v[6:7]
	ds_read_b128 v[4:7], v40
	ds_read_b128 v[30:33], v41
	s_waitcnt lgkmcnt(1)
	v_mov_b32_e32 v37, v5
	s_waitcnt lgkmcnt(0)
	v_pk_mov_b32 v[4:5], v[30:31], v[4:5] op_sel:[1,0]
	v_mov_b32_e32 v36, v30
	v_pk_mul_f32 v[4:5], v[4:5], v[34:35] op_sel:[0,1] op_sel_hi:[1,0]
	v_mov_b32_e32 v126, v32
	v_pk_fma_f32 v[4:5], v[36:37], v[34:35], v[4:5]
	v_add_u32_e32 v36, 0x11830, v13
	v_pk_add_f32 v[4:5], v[124:125], v[4:5]
	v_and_b32_e32 v125, 0xffff0000, v127
	v_lshlrev_b32_e32 v124, 16, v127
	v_mov_b32_e32 v127, v7
	v_pk_mov_b32 v[6:7], v[32:33], v[6:7] op_sel:[1,0]
	v_and_b32_e32 v33, 0xffff0000, v120
	v_pk_mul_f32 v[6:7], v[6:7], v[124:125] op_sel:[0,1] op_sel_hi:[1,0]
	v_lshlrev_b32_e32 v32, 16, v120
	v_pk_fma_f32 v[6:7], v[126:127], v[124:125], v[6:7]
	v_add_u32_e32 v124, 0x12020, v13
	v_pk_add_f32 v[30:31], v[4:5], v[6:7]
	v_add_u32_e32 v4, 0x11820, v13
	ds_read_b128 v[4:7], v4
	ds_read_b128 v[26:29], v124
	v_add_u32_e32 v37, 0x12030, v13
	s_waitcnt lgkmcnt(1)
	v_mov_b32_e32 v35, v5
	s_waitcnt lgkmcnt(0)
	v_pk_mov_b32 v[4:5], v[26:27], v[4:5] op_sel:[1,0]
	v_mov_b32_e32 v34, v26
	v_pk_mul_f32 v[4:5], v[4:5], v[32:33] op_sel:[0,1] op_sel_hi:[1,0]
	v_and_b32_e32 v27, 0xffff0000, v121
	v_lshlrev_b32_e32 v26, 16, v121
	v_mov_b32_e32 v121, v7
	v_pk_mov_b32 v[6:7], v[28:29], v[6:7] op_sel:[1,0]
	v_pk_fma_f32 v[4:5], v[34:35], v[32:33], v[4:5]
	v_mov_b32_e32 v120, v28
	v_pk_mul_f32 v[6:7], v[6:7], v[26:27] op_sel:[0,1] op_sel_hi:[1,0]
	v_pk_add_f32 v[4:5], v[30:31], v[4:5]
	v_pk_fma_f32 v[6:7], v[120:121], v[26:27], v[6:7]
	v_and_b32_e32 v31, 0xffff0000, v122
	v_pk_add_f32 v[120:121], v[4:5], v[6:7]
	ds_read_b128 v[4:7], v36
	ds_read_b128 v[26:29], v37
	v_lshlrev_b32_e32 v30, 16, v122
	s_waitcnt lgkmcnt(1)
	v_mov_b32_e32 v33, v5
	s_waitcnt lgkmcnt(0)
	v_pk_mov_b32 v[4:5], v[26:27], v[4:5] op_sel:[1,0]
	v_mov_b32_e32 v32, v26
	v_pk_mul_f32 v[4:5], v[4:5], v[30:31] op_sel:[0,1] op_sel_hi:[1,0]
	v_mov_b32_e32 v122, v28
	v_pk_fma_f32 v[4:5], v[32:33], v[30:31], v[4:5]
	v_add_u32_e32 v32, 0x11850, v13
	v_pk_add_f32 v[4:5], v[120:121], v[4:5]
	v_and_b32_e32 v121, 0xffff0000, v123
	v_lshlrev_b32_e32 v120, 16, v123
	v_mov_b32_e32 v123, v7
	v_pk_mov_b32 v[6:7], v[28:29], v[6:7] op_sel:[1,0]
	v_and_b32_e32 v29, 0xffff0000, v116
	v_pk_mul_f32 v[6:7], v[6:7], v[120:121] op_sel:[0,1] op_sel_hi:[1,0]
	v_lshlrev_b32_e32 v28, 16, v116
	v_pk_fma_f32 v[6:7], v[122:123], v[120:121], v[6:7]
	v_add_u32_e32 v120, 0x12040, v13
	v_pk_add_f32 v[26:27], v[4:5], v[6:7]
	v_add_u32_e32 v4, 0x11840, v13
	ds_read_b128 v[4:7], v4
	ds_read_b128 v[22:25], v120
	v_add_u32_e32 v33, 0x12050, v13
	s_waitcnt lgkmcnt(1)
	v_mov_b32_e32 v31, v5
	s_waitcnt lgkmcnt(0)
	v_pk_mov_b32 v[4:5], v[22:23], v[4:5] op_sel:[1,0]
	v_mov_b32_e32 v30, v22
	v_pk_mul_f32 v[4:5], v[4:5], v[28:29] op_sel:[0,1] op_sel_hi:[1,0]
	v_and_b32_e32 v23, 0xffff0000, v117
	v_lshlrev_b32_e32 v22, 16, v117
	v_mov_b32_e32 v117, v7
	v_pk_mov_b32 v[6:7], v[24:25], v[6:7] op_sel:[1,0]
	v_pk_fma_f32 v[4:5], v[30:31], v[28:29], v[4:5]
	v_mov_b32_e32 v116, v24
	v_pk_mul_f32 v[6:7], v[6:7], v[22:23] op_sel:[0,1] op_sel_hi:[1,0]
	v_pk_add_f32 v[4:5], v[26:27], v[4:5]
	v_pk_fma_f32 v[6:7], v[116:117], v[22:23], v[6:7]
	v_and_b32_e32 v27, 0xffff0000, v118
	v_pk_add_f32 v[116:117], v[4:5], v[6:7]
	ds_read_b128 v[4:7], v32
	ds_read_b128 v[22:25], v33
	v_lshlrev_b32_e32 v26, 16, v118
	s_waitcnt lgkmcnt(1)
	v_mov_b32_e32 v29, v5
	s_waitcnt lgkmcnt(0)
	v_pk_mov_b32 v[4:5], v[22:23], v[4:5] op_sel:[1,0]
	v_mov_b32_e32 v28, v22
	v_pk_mul_f32 v[4:5], v[4:5], v[26:27] op_sel:[0,1] op_sel_hi:[1,0]
	v_mov_b32_e32 v118, v24
	v_pk_fma_f32 v[4:5], v[28:29], v[26:27], v[4:5]
	v_add_u32_e32 v28, 0x11870, v13
	v_pk_add_f32 v[4:5], v[116:117], v[4:5]
	v_and_b32_e32 v117, 0xffff0000, v119
	v_lshlrev_b32_e32 v116, 16, v119
	v_mov_b32_e32 v119, v7
	v_pk_mov_b32 v[6:7], v[24:25], v[6:7] op_sel:[1,0]
	v_and_b32_e32 v25, 0xffff0000, v112
	v_pk_mul_f32 v[6:7], v[6:7], v[116:117] op_sel:[0,1] op_sel_hi:[1,0]
	v_lshlrev_b32_e32 v24, 16, v112
	v_pk_fma_f32 v[6:7], v[118:119], v[116:117], v[6:7]
	v_add_u32_e32 v116, 0x12060, v13
	v_pk_add_f32 v[22:23], v[4:5], v[6:7]
	v_add_u32_e32 v4, 0x11860, v13
	ds_read_b128 v[4:7], v4
	ds_read_b128 v[18:21], v116
	v_add_u32_e32 v13, 0x12070, v13
	s_waitcnt lgkmcnt(1)
	v_mov_b32_e32 v27, v5
	s_waitcnt lgkmcnt(0)
	v_pk_mov_b32 v[4:5], v[18:19], v[4:5] op_sel:[1,0]
	v_mov_b32_e32 v26, v18
	v_pk_mul_f32 v[4:5], v[4:5], v[24:25] op_sel:[0,1] op_sel_hi:[1,0]
	v_and_b32_e32 v19, 0xffff0000, v113
	v_lshlrev_b32_e32 v18, 16, v113
	v_mov_b32_e32 v113, v7
	v_pk_mov_b32 v[6:7], v[20:21], v[6:7] op_sel:[1,0]
	v_pk_fma_f32 v[4:5], v[26:27], v[24:25], v[4:5]
	v_mov_b32_e32 v112, v20
	v_pk_mul_f32 v[6:7], v[6:7], v[18:19] op_sel:[0,1] op_sel_hi:[1,0]
	v_pk_add_f32 v[4:5], v[22:23], v[4:5]
	v_pk_fma_f32 v[6:7], v[112:113], v[18:19], v[6:7]
	v_and_b32_e32 v23, 0xffff0000, v114
	v_pk_add_f32 v[112:113], v[4:5], v[6:7]
	ds_read_b128 v[4:7], v28
	ds_read_b128 v[18:21], v13
	v_lshlrev_b32_e32 v22, 16, v114
	s_waitcnt lgkmcnt(1)
	v_mov_b32_e32 v25, v5
	s_waitcnt lgkmcnt(0)
	v_pk_mov_b32 v[4:5], v[18:19], v[4:5] op_sel:[1,0]
	v_mov_b32_e32 v24, v18
	v_pk_mul_f32 v[4:5], v[4:5], v[22:23] op_sel:[0,1] op_sel_hi:[1,0]
	v_mov_b32_e32 v114, v20
	v_pk_fma_f32 v[4:5], v[24:25], v[22:23], v[4:5]
	s_nop 0
	v_pk_add_f32 v[4:5], v[112:113], v[4:5]
	v_and_b32_e32 v113, 0xffff0000, v115
	v_lshlrev_b32_e32 v112, 16, v115
	v_mov_b32_e32 v115, v7
	v_pk_mov_b32 v[6:7], v[20:21], v[6:7] op_sel:[1,0]
	s_nop 0
	v_pk_mul_f32 v[6:7], v[6:7], v[112:113] op_sel:[0,1] op_sel_hi:[1,0]
	s_nop 0
	v_pk_fma_f32 v[6:7], v[114:115], v[112:113], v[6:7]
	s_nop 0
	v_pk_add_f32 v[4:5], v[4:5], v[6:7]
	v_mov_b32_e32 v14, v112
	v_mov_b32_e32 v15, v113
	v_mov_b32_e32 v16, v114
	v_mov_b32_e32 v17, v115
	v_add_u32_e32 v13, s5, v8
	v_add_u32_e32 v30, 0x11800, v13
	v_add_u32_e32 v34, 0x12000, v13
	ds_read_b128 v[30:33], v30
	ds_read_b128 v[34:37], v34
	v_add_u32_e32 v40, 0x11810, v13
	v_add_u32_e32 v41, 0x12010, v13
	s_addk_i32 s5, 0x80
	s_waitcnt lgkmcnt(1)
	v_mov_b32_e32 v39, v31
	s_waitcnt lgkmcnt(0)
	v_pk_mov_b32 v[30:31], v[34:35], v[30:31] op_sel:[1,0]
	v_mov_b32_e32 v38, v34
	v_lshl_add_u64 v[2:3], v[2:3], 0, 64
	s_cmpk_eq_i32 s5, 0x200
	s_waitcnt vmcnt(8)
	v_and_b32_e32 v7, 0xffff0000, v140
	v_lshlrev_b32_e32 v6, 16, v140
	v_pk_mul_f32 v[30:31], v[30:31], v[6:7] op_sel:[0,1] op_sel_hi:[1,0]
	v_mov_b32_e32 v140, v36
	v_pk_fma_f32 v[6:7], v[38:39], v[6:7], v[30:31]
	v_pk_mov_b32 v[30:31], v[36:37], v[32:33] op_sel:[1,0]
	v_pk_add_f32 v[4:5], v[4:5], v[6:7]
	v_and_b32_e32 v7, 0xffff0000, v141
	v_lshlrev_b32_e32 v6, 16, v141
	v_mov_b32_e32 v141, v33
	v_pk_mul_f32 v[30:31], v[30:31], v[6:7] op_sel:[0,1] op_sel_hi:[1,0]
	v_and_b32_e32 v35, 0xffff0000, v142
	v_pk_fma_f32 v[6:7], v[140:141], v[6:7], v[30:31]
	v_lshlrev_b32_e32 v34, 16, v142
	v_pk_add_f32 v[140:141], v[4:5], v[6:7]
	ds_read_b128 v[4:7], v40
	ds_read_b128 v[30:33], v41
	s_waitcnt lgkmcnt(1)
	v_mov_b32_e32 v37, v5
	s_waitcnt lgkmcnt(0)
	v_pk_mov_b32 v[4:5], v[30:31], v[4:5] op_sel:[1,0]
	v_mov_b32_e32 v36, v30
	v_pk_mul_f32 v[4:5], v[4:5], v[34:35] op_sel:[0,1] op_sel_hi:[1,0]
	v_mov_b32_e32 v142, v32
	v_pk_fma_f32 v[4:5], v[36:37], v[34:35], v[4:5]
	v_add_u32_e32 v36, 0x11830, v13
	v_pk_add_f32 v[4:5], v[140:141], v[4:5]
	v_and_b32_e32 v141, 0xffff0000, v143
	v_lshlrev_b32_e32 v140, 16, v143
	v_mov_b32_e32 v143, v7
	v_pk_mov_b32 v[6:7], v[32:33], v[6:7] op_sel:[1,0]
	v_and_b32_e32 v33, 0xffff0000, v136
	v_pk_mul_f32 v[6:7], v[6:7], v[140:141] op_sel:[0,1] op_sel_hi:[1,0]
	v_lshlrev_b32_e32 v32, 16, v136
	v_pk_fma_f32 v[6:7], v[142:143], v[140:141], v[6:7]
	v_add_u32_e32 v140, 0x12020, v13
	v_pk_add_f32 v[30:31], v[4:5], v[6:7]
	v_add_u32_e32 v4, 0x11820, v13
	ds_read_b128 v[4:7], v4
	ds_read_b128 v[26:29], v140
	v_add_u32_e32 v37, 0x12030, v13
	s_waitcnt lgkmcnt(1)
	v_mov_b32_e32 v35, v5
	s_waitcnt lgkmcnt(0)
	v_pk_mov_b32 v[4:5], v[26:27], v[4:5] op_sel:[1,0]
	v_mov_b32_e32 v34, v26
	v_pk_mul_f32 v[4:5], v[4:5], v[32:33] op_sel:[0,1] op_sel_hi:[1,0]
	v_and_b32_e32 v27, 0xffff0000, v137
	v_lshlrev_b32_e32 v26, 16, v137
	v_mov_b32_e32 v137, v7
	v_pk_mov_b32 v[6:7], v[28:29], v[6:7] op_sel:[1,0]
	v_pk_fma_f32 v[4:5], v[34:35], v[32:33], v[4:5]
	v_mov_b32_e32 v136, v28
	v_pk_mul_f32 v[6:7], v[6:7], v[26:27] op_sel:[0,1] op_sel_hi:[1,0]
	v_pk_add_f32 v[4:5], v[30:31], v[4:5]
	v_pk_fma_f32 v[6:7], v[136:137], v[26:27], v[6:7]
	v_and_b32_e32 v31, 0xffff0000, v138
	v_pk_add_f32 v[136:137], v[4:5], v[6:7]
	ds_read_b128 v[4:7], v36
	ds_read_b128 v[26:29], v37
	v_lshlrev_b32_e32 v30, 16, v138
	s_waitcnt lgkmcnt(1)
	v_mov_b32_e32 v33, v5
	s_waitcnt lgkmcnt(0)
	v_pk_mov_b32 v[4:5], v[26:27], v[4:5] op_sel:[1,0]
	v_mov_b32_e32 v32, v26
	v_pk_mul_f32 v[4:5], v[4:5], v[30:31] op_sel:[0,1] op_sel_hi:[1,0]
	v_mov_b32_e32 v138, v28
	v_pk_fma_f32 v[4:5], v[32:33], v[30:31], v[4:5]
	v_add_u32_e32 v32, 0x11850, v13
	v_pk_add_f32 v[4:5], v[136:137], v[4:5]
	v_and_b32_e32 v137, 0xffff0000, v139
	v_lshlrev_b32_e32 v136, 16, v139
	v_mov_b32_e32 v139, v7
	v_pk_mov_b32 v[6:7], v[28:29], v[6:7] op_sel:[1,0]
	v_and_b32_e32 v29, 0xffff0000, v132
	v_pk_mul_f32 v[6:7], v[6:7], v[136:137] op_sel:[0,1] op_sel_hi:[1,0]
	v_lshlrev_b32_e32 v28, 16, v132
	v_pk_fma_f32 v[6:7], v[138:139], v[136:137], v[6:7]
	v_add_u32_e32 v136, 0x12040, v13
	v_pk_add_f32 v[26:27], v[4:5], v[6:7]
	v_add_u32_e32 v4, 0x11840, v13
	ds_read_b128 v[4:7], v4
	ds_read_b128 v[22:25], v136
	v_add_u32_e32 v33, 0x12050, v13
	s_waitcnt lgkmcnt(1)
	v_mov_b32_e32 v31, v5
	s_waitcnt lgkmcnt(0)
	v_pk_mov_b32 v[4:5], v[22:23], v[4:5] op_sel:[1,0]
	v_mov_b32_e32 v30, v22
	v_pk_mul_f32 v[4:5], v[4:5], v[28:29] op_sel:[0,1] op_sel_hi:[1,0]
	v_and_b32_e32 v23, 0xffff0000, v133
	v_lshlrev_b32_e32 v22, 16, v133
	v_mov_b32_e32 v133, v7
	v_pk_mov_b32 v[6:7], v[24:25], v[6:7] op_sel:[1,0]
	v_pk_fma_f32 v[4:5], v[30:31], v[28:29], v[4:5]
	v_mov_b32_e32 v132, v24
	v_pk_mul_f32 v[6:7], v[6:7], v[22:23] op_sel:[0,1] op_sel_hi:[1,0]
	v_pk_add_f32 v[4:5], v[26:27], v[4:5]
	v_pk_fma_f32 v[6:7], v[132:133], v[22:23], v[6:7]
	v_and_b32_e32 v27, 0xffff0000, v134
	v_pk_add_f32 v[132:133], v[4:5], v[6:7]
	ds_read_b128 v[4:7], v32
	ds_read_b128 v[22:25], v33
	v_lshlrev_b32_e32 v26, 16, v134
	s_waitcnt lgkmcnt(1)
	v_mov_b32_e32 v29, v5
	s_waitcnt lgkmcnt(0)
	v_pk_mov_b32 v[4:5], v[22:23], v[4:5] op_sel:[1,0]
	v_mov_b32_e32 v28, v22
	v_pk_mul_f32 v[4:5], v[4:5], v[26:27] op_sel:[0,1] op_sel_hi:[1,0]
	v_mov_b32_e32 v134, v24
	v_pk_fma_f32 v[4:5], v[28:29], v[26:27], v[4:5]
	v_add_u32_e32 v28, 0x11870, v13
	v_pk_add_f32 v[4:5], v[132:133], v[4:5]
	v_and_b32_e32 v133, 0xffff0000, v135
	v_lshlrev_b32_e32 v132, 16, v135
	v_mov_b32_e32 v135, v7
	v_pk_mov_b32 v[6:7], v[24:25], v[6:7] op_sel:[1,0]
	v_and_b32_e32 v25, 0xffff0000, v128
	v_pk_mul_f32 v[6:7], v[6:7], v[132:133] op_sel:[0,1] op_sel_hi:[1,0]
	v_lshlrev_b32_e32 v24, 16, v128
	v_pk_fma_f32 v[6:7], v[134:135], v[132:133], v[6:7]
	v_add_u32_e32 v132, 0x12060, v13
	v_pk_add_f32 v[22:23], v[4:5], v[6:7]
	v_add_u32_e32 v4, 0x11860, v13
	ds_read_b128 v[4:7], v4
	ds_read_b128 v[18:21], v132
	v_add_u32_e32 v13, 0x12070, v13
	s_waitcnt lgkmcnt(1)
	v_mov_b32_e32 v27, v5
	s_waitcnt lgkmcnt(0)
	v_pk_mov_b32 v[4:5], v[18:19], v[4:5] op_sel:[1,0]
	v_mov_b32_e32 v26, v18
	v_pk_mul_f32 v[4:5], v[4:5], v[24:25] op_sel:[0,1] op_sel_hi:[1,0]
	v_and_b32_e32 v19, 0xffff0000, v129
	v_lshlrev_b32_e32 v18, 16, v129
	v_mov_b32_e32 v129, v7
	v_pk_mov_b32 v[6:7], v[20:21], v[6:7] op_sel:[1,0]
	v_pk_fma_f32 v[4:5], v[26:27], v[24:25], v[4:5]
	v_mov_b32_e32 v128, v20
	v_pk_mul_f32 v[6:7], v[6:7], v[18:19] op_sel:[0,1] op_sel_hi:[1,0]
	v_pk_add_f32 v[4:5], v[22:23], v[4:5]
	v_pk_fma_f32 v[6:7], v[128:129], v[18:19], v[6:7]
	v_and_b32_e32 v23, 0xffff0000, v130
	v_pk_add_f32 v[128:129], v[4:5], v[6:7]
	ds_read_b128 v[4:7], v28
	ds_read_b128 v[18:21], v13
	v_lshlrev_b32_e32 v22, 16, v130
	s_waitcnt lgkmcnt(1)
	v_mov_b32_e32 v25, v5
	s_waitcnt lgkmcnt(0)
	v_pk_mov_b32 v[4:5], v[18:19], v[4:5] op_sel:[1,0]
	v_mov_b32_e32 v24, v18
	v_pk_mul_f32 v[4:5], v[4:5], v[22:23] op_sel:[0,1] op_sel_hi:[1,0]
	v_mov_b32_e32 v130, v20
	v_pk_fma_f32 v[4:5], v[24:25], v[22:23], v[4:5]
	s_nop 0
	v_pk_add_f32 v[4:5], v[128:129], v[4:5]
	v_and_b32_e32 v129, 0xffff0000, v131
	v_lshlrev_b32_e32 v128, 16, v131
	v_mov_b32_e32 v131, v7
	v_pk_mov_b32 v[6:7], v[20:21], v[6:7] op_sel:[1,0]
	s_nop 0
	v_pk_mul_f32 v[6:7], v[6:7], v[128:129] op_sel:[0,1] op_sel_hi:[1,0]
	s_nop 0
	v_pk_fma_f32 v[6:7], v[130:131], v[128:129], v[6:7]
	s_nop 0
	v_pk_add_f32 v[4:5], v[4:5], v[6:7]
	v_mov_b32_e32 v14, v128
	v_mov_b32_e32 v15, v129
	v_mov_b32_e32 v16, v130
	v_mov_b32_e32 v17, v131
	v_add_u32_e32 v13, s5, v8
	v_add_u32_e32 v30, 0x11800, v13
	v_add_u32_e32 v34, 0x12000, v13
	ds_read_b128 v[30:33], v30
	ds_read_b128 v[34:37], v34
	v_add_u32_e32 v40, 0x11810, v13
	v_add_u32_e32 v41, 0x12010, v13
	s_addk_i32 s5, 0x80
	s_waitcnt lgkmcnt(1)
	v_mov_b32_e32 v39, v31
	s_waitcnt lgkmcnt(0)
	v_pk_mov_b32 v[30:31], v[34:35], v[30:31] op_sel:[1,0]
	v_mov_b32_e32 v38, v34
	v_lshl_add_u64 v[2:3], v[2:3], 0, 64
	s_cmpk_eq_i32 s5, 0x200
	s_waitcnt vmcnt(4)
	v_and_b32_e32 v7, 0xffff0000, v202
	v_lshlrev_b32_e32 v6, 16, v202
	v_pk_mul_f32 v[30:31], v[30:31], v[6:7] op_sel:[0,1] op_sel_hi:[1,0]
	v_mov_b32_e32 v202, v36
	v_pk_fma_f32 v[6:7], v[38:39], v[6:7], v[30:31]
	v_pk_mov_b32 v[30:31], v[36:37], v[32:33] op_sel:[1,0]
	v_pk_add_f32 v[4:5], v[4:5], v[6:7]
	v_and_b32_e32 v7, 0xffff0000, v203
	v_lshlrev_b32_e32 v6, 16, v203
	v_mov_b32_e32 v203, v33
	v_pk_mul_f32 v[30:31], v[30:31], v[6:7] op_sel:[0,1] op_sel_hi:[1,0]
	v_and_b32_e32 v35, 0xffff0000, v204
	v_pk_fma_f32 v[6:7], v[202:203], v[6:7], v[30:31]
	v_lshlrev_b32_e32 v34, 16, v204
	v_pk_add_f32 v[202:203], v[4:5], v[6:7]
	ds_read_b128 v[4:7], v40
	ds_read_b128 v[30:33], v41
	s_waitcnt lgkmcnt(1)
	v_mov_b32_e32 v37, v5
	s_waitcnt lgkmcnt(0)
	v_pk_mov_b32 v[4:5], v[30:31], v[4:5] op_sel:[1,0]
	v_mov_b32_e32 v36, v30
	v_pk_mul_f32 v[4:5], v[4:5], v[34:35] op_sel:[0,1] op_sel_hi:[1,0]
	v_mov_b32_e32 v204, v32
	v_pk_fma_f32 v[4:5], v[36:37], v[34:35], v[4:5]
	v_add_u32_e32 v36, 0x11830, v13
	v_pk_add_f32 v[4:5], v[202:203], v[4:5]
	v_and_b32_e32 v203, 0xffff0000, v205
	v_lshlrev_b32_e32 v202, 16, v205
	v_mov_b32_e32 v205, v7
	v_pk_mov_b32 v[6:7], v[32:33], v[6:7] op_sel:[1,0]
	v_and_b32_e32 v33, 0xffff0000, v198
	v_pk_mul_f32 v[6:7], v[6:7], v[202:203] op_sel:[0,1] op_sel_hi:[1,0]
	v_lshlrev_b32_e32 v32, 16, v198
	v_pk_fma_f32 v[6:7], v[204:205], v[202:203], v[6:7]
	v_add_u32_e32 v202, 0x12020, v13
	v_pk_add_f32 v[30:31], v[4:5], v[6:7]
	v_add_u32_e32 v4, 0x11820, v13
	ds_read_b128 v[4:7], v4
	ds_read_b128 v[26:29], v202
	v_add_u32_e32 v37, 0x12030, v13
	s_waitcnt lgkmcnt(1)
	v_mov_b32_e32 v35, v5
	s_waitcnt lgkmcnt(0)
	v_pk_mov_b32 v[4:5], v[26:27], v[4:5] op_sel:[1,0]
	v_mov_b32_e32 v34, v26
	v_pk_mul_f32 v[4:5], v[4:5], v[32:33] op_sel:[0,1] op_sel_hi:[1,0]
	v_and_b32_e32 v27, 0xffff0000, v199
	v_lshlrev_b32_e32 v26, 16, v199
	v_mov_b32_e32 v199, v7
	v_pk_mov_b32 v[6:7], v[28:29], v[6:7] op_sel:[1,0]
	v_pk_fma_f32 v[4:5], v[34:35], v[32:33], v[4:5]
	v_mov_b32_e32 v198, v28
	v_pk_mul_f32 v[6:7], v[6:7], v[26:27] op_sel:[0,1] op_sel_hi:[1,0]
	v_pk_add_f32 v[4:5], v[30:31], v[4:5]
	v_pk_fma_f32 v[6:7], v[198:199], v[26:27], v[6:7]
	v_and_b32_e32 v31, 0xffff0000, v200
	v_pk_add_f32 v[198:199], v[4:5], v[6:7]
	ds_read_b128 v[4:7], v36
	ds_read_b128 v[26:29], v37
	v_lshlrev_b32_e32 v30, 16, v200
	s_waitcnt lgkmcnt(1)
	v_mov_b32_e32 v33, v5
	s_waitcnt lgkmcnt(0)
	v_pk_mov_b32 v[4:5], v[26:27], v[4:5] op_sel:[1,0]
	v_mov_b32_e32 v32, v26
	v_pk_mul_f32 v[4:5], v[4:5], v[30:31] op_sel:[0,1] op_sel_hi:[1,0]
	v_mov_b32_e32 v200, v28
	v_pk_fma_f32 v[4:5], v[32:33], v[30:31], v[4:5]
	v_add_u32_e32 v32, 0x11850, v13
	v_pk_add_f32 v[4:5], v[198:199], v[4:5]
	v_and_b32_e32 v199, 0xffff0000, v201
	v_lshlrev_b32_e32 v198, 16, v201
	v_mov_b32_e32 v201, v7
	v_pk_mov_b32 v[6:7], v[28:29], v[6:7] op_sel:[1,0]
	v_and_b32_e32 v29, 0xffff0000, v194
	v_pk_mul_f32 v[6:7], v[6:7], v[198:199] op_sel:[0,1] op_sel_hi:[1,0]
	v_lshlrev_b32_e32 v28, 16, v194
	v_pk_fma_f32 v[6:7], v[200:201], v[198:199], v[6:7]
	v_add_u32_e32 v198, 0x12040, v13
	v_pk_add_f32 v[26:27], v[4:5], v[6:7]
	v_add_u32_e32 v4, 0x11840, v13
	ds_read_b128 v[4:7], v4
	ds_read_b128 v[22:25], v198
	v_add_u32_e32 v33, 0x12050, v13
	s_waitcnt lgkmcnt(1)
	v_mov_b32_e32 v31, v5
	s_waitcnt lgkmcnt(0)
	v_pk_mov_b32 v[4:5], v[22:23], v[4:5] op_sel:[1,0]
	v_mov_b32_e32 v30, v22
	v_pk_mul_f32 v[4:5], v[4:5], v[28:29] op_sel:[0,1] op_sel_hi:[1,0]
	v_and_b32_e32 v23, 0xffff0000, v195
	v_lshlrev_b32_e32 v22, 16, v195
	v_mov_b32_e32 v195, v7
	v_pk_mov_b32 v[6:7], v[24:25], v[6:7] op_sel:[1,0]
	v_pk_fma_f32 v[4:5], v[30:31], v[28:29], v[4:5]
	v_mov_b32_e32 v194, v24
	v_pk_mul_f32 v[6:7], v[6:7], v[22:23] op_sel:[0,1] op_sel_hi:[1,0]
	v_pk_add_f32 v[4:5], v[26:27], v[4:5]
	v_pk_fma_f32 v[6:7], v[194:195], v[22:23], v[6:7]
	v_and_b32_e32 v27, 0xffff0000, v196
	v_pk_add_f32 v[194:195], v[4:5], v[6:7]
	ds_read_b128 v[4:7], v32
	ds_read_b128 v[22:25], v33
	v_lshlrev_b32_e32 v26, 16, v196
	s_waitcnt lgkmcnt(1)
	v_mov_b32_e32 v29, v5
	s_waitcnt lgkmcnt(0)
	v_pk_mov_b32 v[4:5], v[22:23], v[4:5] op_sel:[1,0]
	v_mov_b32_e32 v28, v22
	v_pk_mul_f32 v[4:5], v[4:5], v[26:27] op_sel:[0,1] op_sel_hi:[1,0]
	v_mov_b32_e32 v196, v24
	v_pk_fma_f32 v[4:5], v[28:29], v[26:27], v[4:5]
	v_add_u32_e32 v28, 0x11870, v13
	v_pk_add_f32 v[4:5], v[194:195], v[4:5]
	v_and_b32_e32 v195, 0xffff0000, v197
	v_lshlrev_b32_e32 v194, 16, v197
	v_mov_b32_e32 v197, v7
	v_pk_mov_b32 v[6:7], v[24:25], v[6:7] op_sel:[1,0]
	v_and_b32_e32 v25, 0xffff0000, v144
	v_pk_mul_f32 v[6:7], v[6:7], v[194:195] op_sel:[0,1] op_sel_hi:[1,0]
	v_lshlrev_b32_e32 v24, 16, v144
	v_pk_fma_f32 v[6:7], v[196:197], v[194:195], v[6:7]
	v_add_u32_e32 v194, 0x12060, v13
	v_pk_add_f32 v[22:23], v[4:5], v[6:7]
	v_add_u32_e32 v4, 0x11860, v13
	ds_read_b128 v[4:7], v4
	ds_read_b128 v[18:21], v194
	v_add_u32_e32 v13, 0x12070, v13
	s_waitcnt lgkmcnt(1)
	v_mov_b32_e32 v27, v5
	s_waitcnt lgkmcnt(0)
	v_pk_mov_b32 v[4:5], v[18:19], v[4:5] op_sel:[1,0]
	v_mov_b32_e32 v26, v18
	v_pk_mul_f32 v[4:5], v[4:5], v[24:25] op_sel:[0,1] op_sel_hi:[1,0]
	v_and_b32_e32 v19, 0xffff0000, v145
	v_lshlrev_b32_e32 v18, 16, v145
	v_mov_b32_e32 v145, v7
	v_pk_mov_b32 v[6:7], v[20:21], v[6:7] op_sel:[1,0]
	v_pk_fma_f32 v[4:5], v[26:27], v[24:25], v[4:5]
	v_mov_b32_e32 v144, v20
	v_pk_mul_f32 v[6:7], v[6:7], v[18:19] op_sel:[0,1] op_sel_hi:[1,0]
	v_pk_add_f32 v[4:5], v[22:23], v[4:5]
	v_pk_fma_f32 v[6:7], v[144:145], v[18:19], v[6:7]
	v_and_b32_e32 v23, 0xffff0000, v146
	v_pk_add_f32 v[144:145], v[4:5], v[6:7]
	ds_read_b128 v[4:7], v28
	ds_read_b128 v[18:21], v13
	v_lshlrev_b32_e32 v22, 16, v146
	s_waitcnt lgkmcnt(1)
	v_mov_b32_e32 v25, v5
	s_waitcnt lgkmcnt(0)
	v_pk_mov_b32 v[4:5], v[18:19], v[4:5] op_sel:[1,0]
	v_mov_b32_e32 v24, v18
	v_pk_mul_f32 v[4:5], v[4:5], v[22:23] op_sel:[0,1] op_sel_hi:[1,0]
	v_mov_b32_e32 v146, v20
	v_pk_fma_f32 v[4:5], v[24:25], v[22:23], v[4:5]
	s_nop 0
	v_pk_add_f32 v[4:5], v[144:145], v[4:5]
	v_and_b32_e32 v145, 0xffff0000, v147
	v_lshlrev_b32_e32 v144, 16, v147
	v_mov_b32_e32 v147, v7
	v_pk_mov_b32 v[6:7], v[20:21], v[6:7] op_sel:[1,0]
	s_nop 0
	v_pk_mul_f32 v[6:7], v[6:7], v[144:145] op_sel:[0,1] op_sel_hi:[1,0]
	s_nop 0
	v_pk_fma_f32 v[6:7], v[146:147], v[144:145], v[6:7]
	s_nop 0
	v_pk_add_f32 v[4:5], v[4:5], v[6:7]
	v_mov_b32_e32 v14, v144
	v_mov_b32_e32 v15, v145
	v_mov_b32_e32 v16, v146
	v_mov_b32_e32 v17, v147
	v_add_u32_e32 v13, s5, v8
	v_add_u32_e32 v30, 0x11800, v13
	v_add_u32_e32 v34, 0x12000, v13
	ds_read_b128 v[30:33], v30
	ds_read_b128 v[34:37], v34
	v_add_u32_e32 v40, 0x11810, v13
	v_add_u32_e32 v41, 0x12010, v13
	s_addk_i32 s5, 0x80
	s_waitcnt lgkmcnt(1)
	v_mov_b32_e32 v39, v31
	s_waitcnt lgkmcnt(0)
	v_pk_mov_b32 v[30:31], v[34:35], v[30:31] op_sel:[1,0]
	v_mov_b32_e32 v38, v34
	v_lshl_add_u64 v[2:3], v[2:3], 0, 64
	s_cmpk_eq_i32 s5, 0x200
	s_waitcnt vmcnt(0)
	v_and_b32_e32 v7, 0xffff0000, v218
	v_lshlrev_b32_e32 v6, 16, v218
	v_pk_mul_f32 v[30:31], v[30:31], v[6:7] op_sel:[0,1] op_sel_hi:[1,0]
	v_mov_b32_e32 v218, v36
	v_pk_fma_f32 v[6:7], v[38:39], v[6:7], v[30:31]
	v_pk_mov_b32 v[30:31], v[36:37], v[32:33] op_sel:[1,0]
	v_pk_add_f32 v[4:5], v[4:5], v[6:7]
	v_and_b32_e32 v7, 0xffff0000, v219
	v_lshlrev_b32_e32 v6, 16, v219
	v_mov_b32_e32 v219, v33
	v_pk_mul_f32 v[30:31], v[30:31], v[6:7] op_sel:[0,1] op_sel_hi:[1,0]
	v_and_b32_e32 v35, 0xffff0000, v220
	v_pk_fma_f32 v[6:7], v[218:219], v[6:7], v[30:31]
	v_lshlrev_b32_e32 v34, 16, v220
	v_pk_add_f32 v[218:219], v[4:5], v[6:7]
	ds_read_b128 v[4:7], v40
	ds_read_b128 v[30:33], v41
	s_waitcnt lgkmcnt(1)
	v_mov_b32_e32 v37, v5
	s_waitcnt lgkmcnt(0)
	v_pk_mov_b32 v[4:5], v[30:31], v[4:5] op_sel:[1,0]
	v_mov_b32_e32 v36, v30
	v_pk_mul_f32 v[4:5], v[4:5], v[34:35] op_sel:[0,1] op_sel_hi:[1,0]
	v_mov_b32_e32 v220, v32
	v_pk_fma_f32 v[4:5], v[36:37], v[34:35], v[4:5]
	v_add_u32_e32 v36, 0x11830, v13
	v_pk_add_f32 v[4:5], v[218:219], v[4:5]
	v_and_b32_e32 v219, 0xffff0000, v221
	v_lshlrev_b32_e32 v218, 16, v221
	v_mov_b32_e32 v221, v7
	v_pk_mov_b32 v[6:7], v[32:33], v[6:7] op_sel:[1,0]
	v_and_b32_e32 v33, 0xffff0000, v214
	v_pk_mul_f32 v[6:7], v[6:7], v[218:219] op_sel:[0,1] op_sel_hi:[1,0]
	v_lshlrev_b32_e32 v32, 16, v214
	v_pk_fma_f32 v[6:7], v[220:221], v[218:219], v[6:7]
	v_add_u32_e32 v218, 0x12020, v13
	v_pk_add_f32 v[30:31], v[4:5], v[6:7]
	v_add_u32_e32 v4, 0x11820, v13
	ds_read_b128 v[4:7], v4
	ds_read_b128 v[26:29], v218
	v_add_u32_e32 v37, 0x12030, v13
	s_waitcnt lgkmcnt(1)
	v_mov_b32_e32 v35, v5
	s_waitcnt lgkmcnt(0)
	v_pk_mov_b32 v[4:5], v[26:27], v[4:5] op_sel:[1,0]
	v_mov_b32_e32 v34, v26
	v_pk_mul_f32 v[4:5], v[4:5], v[32:33] op_sel:[0,1] op_sel_hi:[1,0]
	v_and_b32_e32 v27, 0xffff0000, v215
	v_lshlrev_b32_e32 v26, 16, v215
	v_mov_b32_e32 v215, v7
	v_pk_mov_b32 v[6:7], v[28:29], v[6:7] op_sel:[1,0]
	v_pk_fma_f32 v[4:5], v[34:35], v[32:33], v[4:5]
	v_mov_b32_e32 v214, v28
	v_pk_mul_f32 v[6:7], v[6:7], v[26:27] op_sel:[0,1] op_sel_hi:[1,0]
	v_pk_add_f32 v[4:5], v[30:31], v[4:5]
	v_pk_fma_f32 v[6:7], v[214:215], v[26:27], v[6:7]
	v_and_b32_e32 v31, 0xffff0000, v216
	v_pk_add_f32 v[214:215], v[4:5], v[6:7]
	ds_read_b128 v[4:7], v36
	ds_read_b128 v[26:29], v37
	v_lshlrev_b32_e32 v30, 16, v216
	s_waitcnt lgkmcnt(1)
	v_mov_b32_e32 v33, v5
	s_waitcnt lgkmcnt(0)
	v_pk_mov_b32 v[4:5], v[26:27], v[4:5] op_sel:[1,0]
	v_mov_b32_e32 v32, v26
	v_pk_mul_f32 v[4:5], v[4:5], v[30:31] op_sel:[0,1] op_sel_hi:[1,0]
	v_mov_b32_e32 v216, v28
	v_pk_fma_f32 v[4:5], v[32:33], v[30:31], v[4:5]
	v_add_u32_e32 v32, 0x11850, v13
	v_pk_add_f32 v[4:5], v[214:215], v[4:5]
	v_and_b32_e32 v215, 0xffff0000, v217
	v_lshlrev_b32_e32 v214, 16, v217
	v_mov_b32_e32 v217, v7
	v_pk_mov_b32 v[6:7], v[28:29], v[6:7] op_sel:[1,0]
	v_and_b32_e32 v29, 0xffff0000, v210
	v_pk_mul_f32 v[6:7], v[6:7], v[214:215] op_sel:[0,1] op_sel_hi:[1,0]
	v_lshlrev_b32_e32 v28, 16, v210
	v_pk_fma_f32 v[6:7], v[216:217], v[214:215], v[6:7]
	v_add_u32_e32 v214, 0x12040, v13
	v_pk_add_f32 v[26:27], v[4:5], v[6:7]
	v_add_u32_e32 v4, 0x11840, v13
	ds_read_b128 v[4:7], v4
	ds_read_b128 v[22:25], v214
	v_add_u32_e32 v33, 0x12050, v13
	s_waitcnt lgkmcnt(1)
	v_mov_b32_e32 v31, v5
	s_waitcnt lgkmcnt(0)
	v_pk_mov_b32 v[4:5], v[22:23], v[4:5] op_sel:[1,0]
	v_mov_b32_e32 v30, v22
	v_pk_mul_f32 v[4:5], v[4:5], v[28:29] op_sel:[0,1] op_sel_hi:[1,0]
	v_and_b32_e32 v23, 0xffff0000, v211
	v_lshlrev_b32_e32 v22, 16, v211
	v_mov_b32_e32 v211, v7
	v_pk_mov_b32 v[6:7], v[24:25], v[6:7] op_sel:[1,0]
	v_pk_fma_f32 v[4:5], v[30:31], v[28:29], v[4:5]
	v_mov_b32_e32 v210, v24
	v_pk_mul_f32 v[6:7], v[6:7], v[22:23] op_sel:[0,1] op_sel_hi:[1,0]
	v_pk_add_f32 v[4:5], v[26:27], v[4:5]
	v_pk_fma_f32 v[6:7], v[210:211], v[22:23], v[6:7]
	v_and_b32_e32 v27, 0xffff0000, v212
	v_pk_add_f32 v[210:211], v[4:5], v[6:7]
	ds_read_b128 v[4:7], v32
	ds_read_b128 v[22:25], v33
	v_lshlrev_b32_e32 v26, 16, v212
	s_waitcnt lgkmcnt(1)
	v_mov_b32_e32 v29, v5
	s_waitcnt lgkmcnt(0)
	v_pk_mov_b32 v[4:5], v[22:23], v[4:5] op_sel:[1,0]
	v_mov_b32_e32 v28, v22
	v_pk_mul_f32 v[4:5], v[4:5], v[26:27] op_sel:[0,1] op_sel_hi:[1,0]
	v_mov_b32_e32 v212, v24
	v_pk_fma_f32 v[4:5], v[28:29], v[26:27], v[4:5]
	v_add_u32_e32 v28, 0x11870, v13
	v_pk_add_f32 v[4:5], v[210:211], v[4:5]
	v_and_b32_e32 v211, 0xffff0000, v213
	v_lshlrev_b32_e32 v210, 16, v213
	v_mov_b32_e32 v213, v7
	v_pk_mov_b32 v[6:7], v[24:25], v[6:7] op_sel:[1,0]
	v_and_b32_e32 v25, 0xffff0000, v206
	v_pk_mul_f32 v[6:7], v[6:7], v[210:211] op_sel:[0,1] op_sel_hi:[1,0]
	v_lshlrev_b32_e32 v24, 16, v206
	v_pk_fma_f32 v[6:7], v[212:213], v[210:211], v[6:7]
	v_add_u32_e32 v210, 0x12060, v13
	v_pk_add_f32 v[22:23], v[4:5], v[6:7]
	v_add_u32_e32 v4, 0x11860, v13
	ds_read_b128 v[4:7], v4
	ds_read_b128 v[18:21], v210
	v_add_u32_e32 v13, 0x12070, v13
	s_waitcnt lgkmcnt(1)
	v_mov_b32_e32 v27, v5
	s_waitcnt lgkmcnt(0)
	v_pk_mov_b32 v[4:5], v[18:19], v[4:5] op_sel:[1,0]
	v_mov_b32_e32 v26, v18
	v_pk_mul_f32 v[4:5], v[4:5], v[24:25] op_sel:[0,1] op_sel_hi:[1,0]
	v_and_b32_e32 v19, 0xffff0000, v207
	v_lshlrev_b32_e32 v18, 16, v207
	v_mov_b32_e32 v207, v7
	v_pk_mov_b32 v[6:7], v[20:21], v[6:7] op_sel:[1,0]
	v_pk_fma_f32 v[4:5], v[26:27], v[24:25], v[4:5]
	v_mov_b32_e32 v206, v20
	v_pk_mul_f32 v[6:7], v[6:7], v[18:19] op_sel:[0,1] op_sel_hi:[1,0]
	v_pk_add_f32 v[4:5], v[22:23], v[4:5]
	v_pk_fma_f32 v[6:7], v[206:207], v[18:19], v[6:7]
	v_and_b32_e32 v23, 0xffff0000, v208
	v_pk_add_f32 v[206:207], v[4:5], v[6:7]
	ds_read_b128 v[4:7], v28
	ds_read_b128 v[18:21], v13
	v_lshlrev_b32_e32 v22, 16, v208
	s_waitcnt lgkmcnt(1)
	v_mov_b32_e32 v25, v5
	s_waitcnt lgkmcnt(0)
	v_pk_mov_b32 v[4:5], v[18:19], v[4:5] op_sel:[1,0]
	v_mov_b32_e32 v24, v18
	v_pk_mul_f32 v[4:5], v[4:5], v[22:23] op_sel:[0,1] op_sel_hi:[1,0]
	v_mov_b32_e32 v208, v20
	v_pk_fma_f32 v[4:5], v[24:25], v[22:23], v[4:5]
	s_nop 0
	v_pk_add_f32 v[4:5], v[206:207], v[4:5]
	v_and_b32_e32 v207, 0xffff0000, v209
	v_lshlrev_b32_e32 v206, 16, v209
	v_mov_b32_e32 v209, v7
	v_pk_mov_b32 v[6:7], v[20:21], v[6:7] op_sel:[1,0]
	s_nop 0
	v_pk_mul_f32 v[6:7], v[6:7], v[206:207] op_sel:[0,1] op_sel_hi:[1,0]
	s_nop 0
	v_pk_fma_f32 v[6:7], v[208:209], v[206:207], v[6:7]
	s_nop 0
	v_pk_add_f32 v[4:5], v[4:5], v[6:7]
	v_mov_b32_e32 v14, v206
	v_mov_b32_e32 v15, v207
	v_mov_b32_e32 v16, v208
	v_mov_b32_e32 v17, v209
	v_and_or_b32 v2, v184, 64, v11
	v_lshlrev_b32_e32 v13, 2, v2
	ds_bpermute_b32 v23, v13, v5
	ds_bpermute_b32 v22, v13, v5 offset:64
	ds_bpermute_b32 v21, v13, v5 offset:128
	ds_bpermute_b32 v20, v13, v5 offset:192
	ds_bpermute_b32 v19, v13, v4
	ds_bpermute_b32 v18, v13, v4 offset:64
	ds_bpermute_b32 v17, v13, v4 offset:128
	v_or_b32_e32 v173, 16, v149
	v_mov_b64_e32 v[4:5], s[30:31]
	v_mad_i64_i32 v[6:7], s[6:7], v173, s65, v[4:5]
	v_mov_b32_e32 v4, 0
	s_mov_b32 s5, 0
	v_or_b32_e32 v14, 64, v13
	v_or_b32_e32 v15, 0x80, v13
	v_or_b32_e32 v16, 0xc0, v13
	v_mad_i64_i32 v[2:3], s[6:7], v173, s65, 0
	v_mov_b32_e32 v5, v4
.LBB0_892:
	global_load_dwordx4 v[112:115], v[6:7], off offset:16
	global_load_dwordx4 v[116:119], v[6:7], off
	global_load_dwordx4 v[120:123], v[6:7], off offset:-16
	global_load_dwordx4 v[124:127], v[6:7], off offset:-32
	global_load_dwordx4 v[128:131], v[6:7], off offset:80
	global_load_dwordx4 v[132:135], v[6:7], off offset:64
	global_load_dwordx4 v[136:139], v[6:7], off offset:48
	global_load_dwordx4 v[140:143], v[6:7], off offset:32
	global_load_dwordx4 v[144:147], v[6:7], off offset:144
	global_load_dwordx4 v[194:197], v[6:7], off offset:128
	global_load_dwordx4 v[198:201], v[6:7], off offset:112
	global_load_dwordx4 v[202:205], v[6:7], off offset:96
	global_load_dwordx4 v[206:209], v[6:7], off offset:208
	global_load_dwordx4 v[210:213], v[6:7], off offset:192
	global_load_dwordx4 v[214:217], v[6:7], off offset:176
	global_load_dwordx4 v[218:221], v[6:7], off offset:160
	v_add_u32_e32 v52, s5, v8
	v_add_u32_e32 v40, 0x11800, v52
	v_add_u32_e32 v44, 0x12000, v52
	ds_read_b128 v[40:43], v40
	ds_read_b128 v[44:47], v44
	v_add_u32_e32 v53, 0x11810, v52
	v_add_u32_e32 v54, 0x12010, v52
	s_addk_i32 s5, 0x80
	s_waitcnt lgkmcnt(1)
	v_mov_b32_e32 v51, v41
	s_waitcnt lgkmcnt(0)
	v_pk_mov_b32 v[40:41], v[44:45], v[40:41] op_sel:[1,0]
	v_mov_b32_e32 v50, v44
	v_lshl_add_u64 v[6:7], v[6:7], 0, 64
	s_cmpk_lg_i32 s5, 0x200
	s_waitcnt vmcnt(12)
	v_and_b32_e32 v49, 0xffff0000, v124
	v_lshlrev_b32_e32 v48, 16, v124
	v_pk_mul_f32 v[40:41], v[40:41], v[48:49] op_sel:[0,1] op_sel_hi:[1,0]
	v_mov_b32_e32 v124, v46
	v_pk_fma_f32 v[40:41], v[50:51], v[48:49], v[40:41]
	s_nop 0
	v_pk_add_f32 v[4:5], v[4:5], v[40:41]
	v_and_b32_e32 v41, 0xffff0000, v125
	v_lshlrev_b32_e32 v40, 16, v125
	v_mov_b32_e32 v125, v43
	v_pk_mov_b32 v[42:43], v[46:47], v[42:43] op_sel:[1,0]
	s_nop 0
	v_pk_mul_f32 v[42:43], v[42:43], v[40:41] op_sel:[0,1] op_sel_hi:[1,0]
	s_nop 0
	v_pk_fma_f32 v[124:125], v[124:125], v[40:41], v[42:43]
	ds_read_b128 v[40:43], v53
	ds_read_b128 v[44:47], v54
	v_pk_add_f32 v[4:5], v[4:5], v[124:125]
	v_and_b32_e32 v125, 0xffff0000, v126
	v_lshlrev_b32_e32 v124, 16, v126
	s_waitcnt lgkmcnt(1)
	v_mov_b32_e32 v49, v41
	s_waitcnt lgkmcnt(0)
	v_pk_mov_b32 v[40:41], v[44:45], v[40:41] op_sel:[1,0]
	v_mov_b32_e32 v48, v44
	v_pk_mul_f32 v[40:41], v[40:41], v[124:125] op_sel:[0,1] op_sel_hi:[1,0]
	v_mov_b32_e32 v126, v46
	v_pk_fma_f32 v[124:125], v[48:49], v[124:125], v[40:41]
	v_pk_mov_b32 v[40:41], v[46:47], v[42:43] op_sel:[1,0]
	v_pk_add_f32 v[4:5], v[4:5], v[124:125]
	v_and_b32_e32 v125, 0xffff0000, v127
	v_lshlrev_b32_e32 v124, 16, v127
	v_mov_b32_e32 v127, v43
	v_pk_mul_f32 v[40:41], v[40:41], v[124:125] op_sel:[0,1] op_sel_hi:[1,0]
	v_and_b32_e32 v45, 0xffff0000, v120
	v_pk_fma_f32 v[124:125], v[126:127], v[124:125], v[40:41]
	v_add_u32_e32 v40, 0x12020, v52
	v_pk_add_f32 v[4:5], v[4:5], v[124:125]
	v_add_u32_e32 v124, 0x11820, v52
	ds_read_b128 v[36:39], v124
	ds_read_b128 v[40:43], v40
	v_lshlrev_b32_e32 v44, 16, v120
	v_add_u32_e32 v48, 0x11830, v52
	v_add_u32_e32 v49, 0x12030, v52
	s_waitcnt lgkmcnt(1)
	v_mov_b32_e32 v47, v37
	s_waitcnt lgkmcnt(0)
	v_pk_mov_b32 v[36:37], v[40:41], v[36:37] op_sel:[1,0]
	v_mov_b32_e32 v46, v40
	v_pk_mul_f32 v[36:37], v[36:37], v[44:45] op_sel:[0,1] op_sel_hi:[1,0]
	v_mov_b32_e32 v120, v42
	v_pk_fma_f32 v[36:37], v[46:47], v[44:45], v[36:37]
	s_nop 0
	v_pk_add_f32 v[4:5], v[4:5], v[36:37]
	v_and_b32_e32 v37, 0xffff0000, v121
	v_lshlrev_b32_e32 v36, 16, v121
	v_mov_b32_e32 v121, v39
	v_pk_mov_b32 v[38:39], v[42:43], v[38:39] op_sel:[1,0]
	s_nop 0
	v_pk_mul_f32 v[38:39], v[38:39], v[36:37] op_sel:[0,1] op_sel_hi:[1,0]
	s_nop 0
	v_pk_fma_f32 v[120:121], v[120:121], v[36:37], v[38:39]
	ds_read_b128 v[36:39], v48
	ds_read_b128 v[40:43], v49
	v_pk_add_f32 v[4:5], v[4:5], v[120:121]
	v_and_b32_e32 v121, 0xffff0000, v122
	v_lshlrev_b32_e32 v120, 16, v122
	s_waitcnt lgkmcnt(1)
	v_mov_b32_e32 v45, v37
	s_waitcnt lgkmcnt(0)
	v_pk_mov_b32 v[36:37], v[40:41], v[36:37] op_sel:[1,0]
	v_mov_b32_e32 v44, v40
	v_pk_mul_f32 v[36:37], v[36:37], v[120:121] op_sel:[0,1] op_sel_hi:[1,0]
	v_mov_b32_e32 v122, v42
	v_pk_fma_f32 v[120:121], v[44:45], v[120:121], v[36:37]
	v_pk_mov_b32 v[36:37], v[42:43], v[38:39] op_sel:[1,0]
	v_pk_add_f32 v[4:5], v[4:5], v[120:121]
	v_and_b32_e32 v121, 0xffff0000, v123
	v_lshlrev_b32_e32 v120, 16, v123
	v_mov_b32_e32 v123, v39
	v_pk_mul_f32 v[36:37], v[36:37], v[120:121] op_sel:[0,1] op_sel_hi:[1,0]
	v_and_b32_e32 v41, 0xffff0000, v116
	v_pk_fma_f32 v[120:121], v[122:123], v[120:121], v[36:37]
	v_add_u32_e32 v36, 0x12040, v52
	v_pk_add_f32 v[4:5], v[4:5], v[120:121]
	v_add_u32_e32 v120, 0x11840, v52
	ds_read_b128 v[32:35], v120
	ds_read_b128 v[36:39], v36
	v_lshlrev_b32_e32 v40, 16, v116
	v_add_u32_e32 v44, 0x11850, v52
	v_add_u32_e32 v45, 0x12050, v52
	s_waitcnt lgkmcnt(1)
	v_mov_b32_e32 v43, v33
	s_waitcnt lgkmcnt(0)
	v_pk_mov_b32 v[32:33], v[36:37], v[32:33] op_sel:[1,0]
	v_mov_b32_e32 v42, v36
	v_pk_mul_f32 v[32:33], v[32:33], v[40:41] op_sel:[0,1] op_sel_hi:[1,0]
	v_mov_b32_e32 v116, v38
	v_pk_fma_f32 v[32:33], v[42:43], v[40:41], v[32:33]
	s_nop 0
	v_pk_add_f32 v[4:5], v[4:5], v[32:33]
	v_and_b32_e32 v33, 0xffff0000, v117
	v_lshlrev_b32_e32 v32, 16, v117
	v_mov_b32_e32 v117, v35
	v_pk_mov_b32 v[34:35], v[38:39], v[34:35] op_sel:[1,0]
	s_nop 0
	v_pk_mul_f32 v[34:35], v[34:35], v[32:33] op_sel:[0,1] op_sel_hi:[1,0]
	s_nop 0
	v_pk_fma_f32 v[116:117], v[116:117], v[32:33], v[34:35]
	ds_read_b128 v[32:35], v44
	ds_read_b128 v[36:39], v45
	v_pk_add_f32 v[4:5], v[4:5], v[116:117]
	v_and_b32_e32 v117, 0xffff0000, v118
	v_lshlrev_b32_e32 v116, 16, v118
	s_waitcnt lgkmcnt(1)
	v_mov_b32_e32 v41, v33
	s_waitcnt lgkmcnt(0)
	v_pk_mov_b32 v[32:33], v[36:37], v[32:33] op_sel:[1,0]
	v_mov_b32_e32 v40, v36
	v_pk_mul_f32 v[32:33], v[32:33], v[116:117] op_sel:[0,1] op_sel_hi:[1,0]
	v_mov_b32_e32 v118, v38
	v_pk_fma_f32 v[116:117], v[40:41], v[116:117], v[32:33]
	v_pk_mov_b32 v[32:33], v[38:39], v[34:35] op_sel:[1,0]
	v_pk_add_f32 v[4:5], v[4:5], v[116:117]
	v_and_b32_e32 v117, 0xffff0000, v119
	v_lshlrev_b32_e32 v116, 16, v119
	v_mov_b32_e32 v119, v35
	v_pk_mul_f32 v[32:33], v[32:33], v[116:117] op_sel:[0,1] op_sel_hi:[1,0]
	v_and_b32_e32 v37, 0xffff0000, v112
	v_pk_fma_f32 v[116:117], v[118:119], v[116:117], v[32:33]
	v_add_u32_e32 v32, 0x12060, v52
	v_pk_add_f32 v[4:5], v[4:5], v[116:117]
	v_add_u32_e32 v116, 0x11860, v52
	ds_read_b128 v[28:31], v116
	ds_read_b128 v[32:35], v32
	v_lshlrev_b32_e32 v36, 16, v112
	v_add_u32_e32 v40, 0x11870, v52
	v_add_u32_e32 v41, 0x12070, v52
	s_waitcnt lgkmcnt(1)
	v_mov_b32_e32 v39, v29
	s_waitcnt lgkmcnt(0)
	v_pk_mov_b32 v[28:29], v[32:33], v[28:29] op_sel:[1,0]
	v_mov_b32_e32 v38, v32
	v_pk_mul_f32 v[28:29], v[28:29], v[36:37] op_sel:[0,1] op_sel_hi:[1,0]
	v_mov_b32_e32 v112, v34
	v_pk_fma_f32 v[28:29], v[38:39], v[36:37], v[28:29]
	s_nop 0
	v_pk_add_f32 v[4:5], v[4:5], v[28:29]
	v_and_b32_e32 v29, 0xffff0000, v113
	v_lshlrev_b32_e32 v28, 16, v113
	v_mov_b32_e32 v113, v31
	v_pk_mov_b32 v[30:31], v[34:35], v[30:31] op_sel:[1,0]
	s_nop 0
	v_pk_mul_f32 v[30:31], v[30:31], v[28:29] op_sel:[0,1] op_sel_hi:[1,0]
	s_nop 0
	v_pk_fma_f32 v[112:113], v[112:113], v[28:29], v[30:31]
	ds_read_b128 v[28:31], v40
	ds_read_b128 v[32:35], v41
	v_pk_add_f32 v[4:5], v[4:5], v[112:113]
	v_and_b32_e32 v113, 0xffff0000, v114
	v_lshlrev_b32_e32 v112, 16, v114
	s_waitcnt lgkmcnt(1)
	v_mov_b32_e32 v37, v29
	s_waitcnt lgkmcnt(0)
	v_pk_mov_b32 v[28:29], v[32:33], v[28:29] op_sel:[1,0]
	v_mov_b32_e32 v36, v32
	v_pk_mul_f32 v[28:29], v[28:29], v[112:113] op_sel:[0,1] op_sel_hi:[1,0]
	v_mov_b32_e32 v114, v34
	v_pk_fma_f32 v[112:113], v[36:37], v[112:113], v[28:29]
	v_pk_mov_b32 v[28:29], v[34:35], v[30:31] op_sel:[1,0]
	v_pk_add_f32 v[4:5], v[4:5], v[112:113]
	v_and_b32_e32 v113, 0xffff0000, v115
	v_lshlrev_b32_e32 v112, 16, v115
	v_mov_b32_e32 v115, v31
	v_pk_mul_f32 v[28:29], v[28:29], v[112:113] op_sel:[0,1] op_sel_hi:[1,0]
	s_nop 0
	v_pk_fma_f32 v[112:113], v[114:115], v[112:113], v[28:29]
	s_nop 0
	v_pk_add_f32 v[4:5], v[4:5], v[112:113]
	v_mov_b32_e32 v24, v112
	v_mov_b32_e32 v25, v113
	v_mov_b32_e32 v26, v114
	v_mov_b32_e32 v27, v115
	v_add_u32_e32 v52, s5, v8
	v_add_u32_e32 v40, 0x11800, v52
	v_add_u32_e32 v44, 0x12000, v52
	ds_read_b128 v[40:43], v40
	ds_read_b128 v[44:47], v44
	v_add_u32_e32 v53, 0x11810, v52
	v_add_u32_e32 v54, 0x12010, v52
	s_addk_i32 s5, 0x80
	s_waitcnt lgkmcnt(1)
	v_mov_b32_e32 v51, v41
	s_waitcnt lgkmcnt(0)
	v_pk_mov_b32 v[40:41], v[44:45], v[40:41] op_sel:[1,0]
	v_mov_b32_e32 v50, v44
	v_lshl_add_u64 v[6:7], v[6:7], 0, 64
	s_cmpk_lg_i32 s5, 0x200
	s_waitcnt vmcnt(8)
	v_and_b32_e32 v49, 0xffff0000, v140
	v_lshlrev_b32_e32 v48, 16, v140
	v_pk_mul_f32 v[40:41], v[40:41], v[48:49] op_sel:[0,1] op_sel_hi:[1,0]
	v_mov_b32_e32 v140, v46
	v_pk_fma_f32 v[40:41], v[50:51], v[48:49], v[40:41]
	s_nop 0
	v_pk_add_f32 v[4:5], v[4:5], v[40:41]
	v_and_b32_e32 v41, 0xffff0000, v141
	v_lshlrev_b32_e32 v40, 16, v141
	v_mov_b32_e32 v141, v43
	v_pk_mov_b32 v[42:43], v[46:47], v[42:43] op_sel:[1,0]
	s_nop 0
	v_pk_mul_f32 v[42:43], v[42:43], v[40:41] op_sel:[0,1] op_sel_hi:[1,0]
	s_nop 0
	v_pk_fma_f32 v[140:141], v[140:141], v[40:41], v[42:43]
	ds_read_b128 v[40:43], v53
	ds_read_b128 v[44:47], v54
	v_pk_add_f32 v[4:5], v[4:5], v[140:141]
	v_and_b32_e32 v141, 0xffff0000, v142
	v_lshlrev_b32_e32 v140, 16, v142
	s_waitcnt lgkmcnt(1)
	v_mov_b32_e32 v49, v41
	s_waitcnt lgkmcnt(0)
	v_pk_mov_b32 v[40:41], v[44:45], v[40:41] op_sel:[1,0]
	v_mov_b32_e32 v48, v44
	v_pk_mul_f32 v[40:41], v[40:41], v[140:141] op_sel:[0,1] op_sel_hi:[1,0]
	v_mov_b32_e32 v142, v46
	v_pk_fma_f32 v[140:141], v[48:49], v[140:141], v[40:41]
	v_pk_mov_b32 v[40:41], v[46:47], v[42:43] op_sel:[1,0]
	v_pk_add_f32 v[4:5], v[4:5], v[140:141]
	v_and_b32_e32 v141, 0xffff0000, v143
	v_lshlrev_b32_e32 v140, 16, v143
	v_mov_b32_e32 v143, v43
	v_pk_mul_f32 v[40:41], v[40:41], v[140:141] op_sel:[0,1] op_sel_hi:[1,0]
	v_and_b32_e32 v45, 0xffff0000, v136
	v_pk_fma_f32 v[140:141], v[142:143], v[140:141], v[40:41]
	v_add_u32_e32 v40, 0x12020, v52
	v_pk_add_f32 v[4:5], v[4:5], v[140:141]
	v_add_u32_e32 v140, 0x11820, v52
	ds_read_b128 v[36:39], v140
	ds_read_b128 v[40:43], v40
	v_lshlrev_b32_e32 v44, 16, v136
	v_add_u32_e32 v48, 0x11830, v52
	v_add_u32_e32 v49, 0x12030, v52
	s_waitcnt lgkmcnt(1)
	v_mov_b32_e32 v47, v37
	s_waitcnt lgkmcnt(0)
	v_pk_mov_b32 v[36:37], v[40:41], v[36:37] op_sel:[1,0]
	v_mov_b32_e32 v46, v40
	v_pk_mul_f32 v[36:37], v[36:37], v[44:45] op_sel:[0,1] op_sel_hi:[1,0]
	v_mov_b32_e32 v136, v42
	v_pk_fma_f32 v[36:37], v[46:47], v[44:45], v[36:37]
	s_nop 0
	v_pk_add_f32 v[4:5], v[4:5], v[36:37]
	v_and_b32_e32 v37, 0xffff0000, v137
	v_lshlrev_b32_e32 v36, 16, v137
	v_mov_b32_e32 v137, v39
	v_pk_mov_b32 v[38:39], v[42:43], v[38:39] op_sel:[1,0]
	s_nop 0
	v_pk_mul_f32 v[38:39], v[38:39], v[36:37] op_sel:[0,1] op_sel_hi:[1,0]
	s_nop 0
	v_pk_fma_f32 v[136:137], v[136:137], v[36:37], v[38:39]
	ds_read_b128 v[36:39], v48
	ds_read_b128 v[40:43], v49
	v_pk_add_f32 v[4:5], v[4:5], v[136:137]
	v_and_b32_e32 v137, 0xffff0000, v138
	v_lshlrev_b32_e32 v136, 16, v138
	s_waitcnt lgkmcnt(1)
	v_mov_b32_e32 v45, v37
	s_waitcnt lgkmcnt(0)
	v_pk_mov_b32 v[36:37], v[40:41], v[36:37] op_sel:[1,0]
	v_mov_b32_e32 v44, v40
	v_pk_mul_f32 v[36:37], v[36:37], v[136:137] op_sel:[0,1] op_sel_hi:[1,0]
	v_mov_b32_e32 v138, v42
	v_pk_fma_f32 v[136:137], v[44:45], v[136:137], v[36:37]
	v_pk_mov_b32 v[36:37], v[42:43], v[38:39] op_sel:[1,0]
	v_pk_add_f32 v[4:5], v[4:5], v[136:137]
	v_and_b32_e32 v137, 0xffff0000, v139
	v_lshlrev_b32_e32 v136, 16, v139
	v_mov_b32_e32 v139, v39
	v_pk_mul_f32 v[36:37], v[36:37], v[136:137] op_sel:[0,1] op_sel_hi:[1,0]
	v_and_b32_e32 v41, 0xffff0000, v132
	v_pk_fma_f32 v[136:137], v[138:139], v[136:137], v[36:37]
	v_add_u32_e32 v36, 0x12040, v52
	v_pk_add_f32 v[4:5], v[4:5], v[136:137]
	v_add_u32_e32 v136, 0x11840, v52
	ds_read_b128 v[32:35], v136
	ds_read_b128 v[36:39], v36
	v_lshlrev_b32_e32 v40, 16, v132
	v_add_u32_e32 v44, 0x11850, v52
	v_add_u32_e32 v45, 0x12050, v52
	s_waitcnt lgkmcnt(1)
	v_mov_b32_e32 v43, v33
	s_waitcnt lgkmcnt(0)
	v_pk_mov_b32 v[32:33], v[36:37], v[32:33] op_sel:[1,0]
	v_mov_b32_e32 v42, v36
	v_pk_mul_f32 v[32:33], v[32:33], v[40:41] op_sel:[0,1] op_sel_hi:[1,0]
	v_mov_b32_e32 v132, v38
	v_pk_fma_f32 v[32:33], v[42:43], v[40:41], v[32:33]
	s_nop 0
	v_pk_add_f32 v[4:5], v[4:5], v[32:33]
	v_and_b32_e32 v33, 0xffff0000, v133
	v_lshlrev_b32_e32 v32, 16, v133
	v_mov_b32_e32 v133, v35
	v_pk_mov_b32 v[34:35], v[38:39], v[34:35] op_sel:[1,0]
	s_nop 0
	v_pk_mul_f32 v[34:35], v[34:35], v[32:33] op_sel:[0,1] op_sel_hi:[1,0]
	s_nop 0
	v_pk_fma_f32 v[132:133], v[132:133], v[32:33], v[34:35]
	ds_read_b128 v[32:35], v44
	ds_read_b128 v[36:39], v45
	v_pk_add_f32 v[4:5], v[4:5], v[132:133]
	v_and_b32_e32 v133, 0xffff0000, v134
	v_lshlrev_b32_e32 v132, 16, v134
	s_waitcnt lgkmcnt(1)
	v_mov_b32_e32 v41, v33
	s_waitcnt lgkmcnt(0)
	v_pk_mov_b32 v[32:33], v[36:37], v[32:33] op_sel:[1,0]
	v_mov_b32_e32 v40, v36
	v_pk_mul_f32 v[32:33], v[32:33], v[132:133] op_sel:[0,1] op_sel_hi:[1,0]
	v_mov_b32_e32 v134, v38
	v_pk_fma_f32 v[132:133], v[40:41], v[132:133], v[32:33]
	v_pk_mov_b32 v[32:33], v[38:39], v[34:35] op_sel:[1,0]
	v_pk_add_f32 v[4:5], v[4:5], v[132:133]
	v_and_b32_e32 v133, 0xffff0000, v135
	v_lshlrev_b32_e32 v132, 16, v135
	v_mov_b32_e32 v135, v35
	v_pk_mul_f32 v[32:33], v[32:33], v[132:133] op_sel:[0,1] op_sel_hi:[1,0]
	v_and_b32_e32 v37, 0xffff0000, v128
	v_pk_fma_f32 v[132:133], v[134:135], v[132:133], v[32:33]
	v_add_u32_e32 v32, 0x12060, v52
	v_pk_add_f32 v[4:5], v[4:5], v[132:133]
	v_add_u32_e32 v132, 0x11860, v52
	ds_read_b128 v[28:31], v132
	ds_read_b128 v[32:35], v32
	v_lshlrev_b32_e32 v36, 16, v128
	v_add_u32_e32 v40, 0x11870, v52
	v_add_u32_e32 v41, 0x12070, v52
	s_waitcnt lgkmcnt(1)
	v_mov_b32_e32 v39, v29
	s_waitcnt lgkmcnt(0)
	v_pk_mov_b32 v[28:29], v[32:33], v[28:29] op_sel:[1,0]
	v_mov_b32_e32 v38, v32
	v_pk_mul_f32 v[28:29], v[28:29], v[36:37] op_sel:[0,1] op_sel_hi:[1,0]
	v_mov_b32_e32 v128, v34
	v_pk_fma_f32 v[28:29], v[38:39], v[36:37], v[28:29]
	s_nop 0
	v_pk_add_f32 v[4:5], v[4:5], v[28:29]
	v_and_b32_e32 v29, 0xffff0000, v129
	v_lshlrev_b32_e32 v28, 16, v129
	v_mov_b32_e32 v129, v31
	v_pk_mov_b32 v[30:31], v[34:35], v[30:31] op_sel:[1,0]
	s_nop 0
	v_pk_mul_f32 v[30:31], v[30:31], v[28:29] op_sel:[0,1] op_sel_hi:[1,0]
	s_nop 0
	v_pk_fma_f32 v[128:129], v[128:129], v[28:29], v[30:31]
	ds_read_b128 v[28:31], v40
	ds_read_b128 v[32:35], v41
	v_pk_add_f32 v[4:5], v[4:5], v[128:129]
	v_and_b32_e32 v129, 0xffff0000, v130
	v_lshlrev_b32_e32 v128, 16, v130
	s_waitcnt lgkmcnt(1)
	v_mov_b32_e32 v37, v29
	s_waitcnt lgkmcnt(0)
	v_pk_mov_b32 v[28:29], v[32:33], v[28:29] op_sel:[1,0]
	v_mov_b32_e32 v36, v32
	v_pk_mul_f32 v[28:29], v[28:29], v[128:129] op_sel:[0,1] op_sel_hi:[1,0]
	v_mov_b32_e32 v130, v34
	v_pk_fma_f32 v[128:129], v[36:37], v[128:129], v[28:29]
	v_pk_mov_b32 v[28:29], v[34:35], v[30:31] op_sel:[1,0]
	v_pk_add_f32 v[4:5], v[4:5], v[128:129]
	v_and_b32_e32 v129, 0xffff0000, v131
	v_lshlrev_b32_e32 v128, 16, v131
	v_mov_b32_e32 v131, v31
	v_pk_mul_f32 v[28:29], v[28:29], v[128:129] op_sel:[0,1] op_sel_hi:[1,0]
	s_nop 0
	v_pk_fma_f32 v[128:129], v[130:131], v[128:129], v[28:29]
	s_nop 0
	v_pk_add_f32 v[4:5], v[4:5], v[128:129]
	v_mov_b32_e32 v24, v128
	v_mov_b32_e32 v25, v129
	v_mov_b32_e32 v26, v130
	v_mov_b32_e32 v27, v131
	v_add_u32_e32 v52, s5, v8
	v_add_u32_e32 v40, 0x11800, v52
	v_add_u32_e32 v44, 0x12000, v52
	ds_read_b128 v[40:43], v40
	ds_read_b128 v[44:47], v44
	v_add_u32_e32 v53, 0x11810, v52
	v_add_u32_e32 v54, 0x12010, v52
	s_addk_i32 s5, 0x80
	s_waitcnt lgkmcnt(1)
	v_mov_b32_e32 v51, v41
	s_waitcnt lgkmcnt(0)
	v_pk_mov_b32 v[40:41], v[44:45], v[40:41] op_sel:[1,0]
	v_mov_b32_e32 v50, v44
	v_lshl_add_u64 v[6:7], v[6:7], 0, 64
	s_cmpk_lg_i32 s5, 0x200
	s_waitcnt vmcnt(4)
	v_and_b32_e32 v49, 0xffff0000, v202
	v_lshlrev_b32_e32 v48, 16, v202
	v_pk_mul_f32 v[40:41], v[40:41], v[48:49] op_sel:[0,1] op_sel_hi:[1,0]
	v_mov_b32_e32 v202, v46
	v_pk_fma_f32 v[40:41], v[50:51], v[48:49], v[40:41]
	s_nop 0
	v_pk_add_f32 v[4:5], v[4:5], v[40:41]
	v_and_b32_e32 v41, 0xffff0000, v203
	v_lshlrev_b32_e32 v40, 16, v203
	v_mov_b32_e32 v203, v43
	v_pk_mov_b32 v[42:43], v[46:47], v[42:43] op_sel:[1,0]
	s_nop 0
	v_pk_mul_f32 v[42:43], v[42:43], v[40:41] op_sel:[0,1] op_sel_hi:[1,0]
	s_nop 0
	v_pk_fma_f32 v[202:203], v[202:203], v[40:41], v[42:43]
	ds_read_b128 v[40:43], v53
	ds_read_b128 v[44:47], v54
	v_pk_add_f32 v[4:5], v[4:5], v[202:203]
	v_and_b32_e32 v203, 0xffff0000, v204
	v_lshlrev_b32_e32 v202, 16, v204
	s_waitcnt lgkmcnt(1)
	v_mov_b32_e32 v49, v41
	s_waitcnt lgkmcnt(0)
	v_pk_mov_b32 v[40:41], v[44:45], v[40:41] op_sel:[1,0]
	v_mov_b32_e32 v48, v44
	v_pk_mul_f32 v[40:41], v[40:41], v[202:203] op_sel:[0,1] op_sel_hi:[1,0]
	v_mov_b32_e32 v204, v46
	v_pk_fma_f32 v[202:203], v[48:49], v[202:203], v[40:41]
	v_pk_mov_b32 v[40:41], v[46:47], v[42:43] op_sel:[1,0]
	v_pk_add_f32 v[4:5], v[4:5], v[202:203]
	v_and_b32_e32 v203, 0xffff0000, v205
	v_lshlrev_b32_e32 v202, 16, v205
	v_mov_b32_e32 v205, v43
	v_pk_mul_f32 v[40:41], v[40:41], v[202:203] op_sel:[0,1] op_sel_hi:[1,0]
	v_and_b32_e32 v45, 0xffff0000, v198
	v_pk_fma_f32 v[202:203], v[204:205], v[202:203], v[40:41]
	v_add_u32_e32 v40, 0x12020, v52
	v_pk_add_f32 v[4:5], v[4:5], v[202:203]
	v_add_u32_e32 v202, 0x11820, v52
	ds_read_b128 v[36:39], v202
	ds_read_b128 v[40:43], v40
	v_lshlrev_b32_e32 v44, 16, v198
	v_add_u32_e32 v48, 0x11830, v52
	v_add_u32_e32 v49, 0x12030, v52
	s_waitcnt lgkmcnt(1)
	v_mov_b32_e32 v47, v37
	s_waitcnt lgkmcnt(0)
	v_pk_mov_b32 v[36:37], v[40:41], v[36:37] op_sel:[1,0]
	v_mov_b32_e32 v46, v40
	v_pk_mul_f32 v[36:37], v[36:37], v[44:45] op_sel:[0,1] op_sel_hi:[1,0]
	v_mov_b32_e32 v198, v42
	v_pk_fma_f32 v[36:37], v[46:47], v[44:45], v[36:37]
	s_nop 0
	v_pk_add_f32 v[4:5], v[4:5], v[36:37]
	v_and_b32_e32 v37, 0xffff0000, v199
	v_lshlrev_b32_e32 v36, 16, v199
	v_mov_b32_e32 v199, v39
	v_pk_mov_b32 v[38:39], v[42:43], v[38:39] op_sel:[1,0]
	s_nop 0
	v_pk_mul_f32 v[38:39], v[38:39], v[36:37] op_sel:[0,1] op_sel_hi:[1,0]
	s_nop 0
	v_pk_fma_f32 v[198:199], v[198:199], v[36:37], v[38:39]
	ds_read_b128 v[36:39], v48
	ds_read_b128 v[40:43], v49
	v_pk_add_f32 v[4:5], v[4:5], v[198:199]
	v_and_b32_e32 v199, 0xffff0000, v200
	v_lshlrev_b32_e32 v198, 16, v200
	s_waitcnt lgkmcnt(1)
	v_mov_b32_e32 v45, v37
	s_waitcnt lgkmcnt(0)
	v_pk_mov_b32 v[36:37], v[40:41], v[36:37] op_sel:[1,0]
	v_mov_b32_e32 v44, v40
	v_pk_mul_f32 v[36:37], v[36:37], v[198:199] op_sel:[0,1] op_sel_hi:[1,0]
	v_mov_b32_e32 v200, v42
	v_pk_fma_f32 v[198:199], v[44:45], v[198:199], v[36:37]
	v_pk_mov_b32 v[36:37], v[42:43], v[38:39] op_sel:[1,0]
	v_pk_add_f32 v[4:5], v[4:5], v[198:199]
	v_and_b32_e32 v199, 0xffff0000, v201
	v_lshlrev_b32_e32 v198, 16, v201
	v_mov_b32_e32 v201, v39
	v_pk_mul_f32 v[36:37], v[36:37], v[198:199] op_sel:[0,1] op_sel_hi:[1,0]
	v_and_b32_e32 v41, 0xffff0000, v194
	v_pk_fma_f32 v[198:199], v[200:201], v[198:199], v[36:37]
	v_add_u32_e32 v36, 0x12040, v52
	v_pk_add_f32 v[4:5], v[4:5], v[198:199]
	v_add_u32_e32 v198, 0x11840, v52
	ds_read_b128 v[32:35], v198
	ds_read_b128 v[36:39], v36
	v_lshlrev_b32_e32 v40, 16, v194
	v_add_u32_e32 v44, 0x11850, v52
	v_add_u32_e32 v45, 0x12050, v52
	s_waitcnt lgkmcnt(1)
	v_mov_b32_e32 v43, v33
	s_waitcnt lgkmcnt(0)
	v_pk_mov_b32 v[32:33], v[36:37], v[32:33] op_sel:[1,0]
	v_mov_b32_e32 v42, v36
	v_pk_mul_f32 v[32:33], v[32:33], v[40:41] op_sel:[0,1] op_sel_hi:[1,0]
	v_mov_b32_e32 v194, v38
	v_pk_fma_f32 v[32:33], v[42:43], v[40:41], v[32:33]
	s_nop 0
	v_pk_add_f32 v[4:5], v[4:5], v[32:33]
	v_and_b32_e32 v33, 0xffff0000, v195
	v_lshlrev_b32_e32 v32, 16, v195
	v_mov_b32_e32 v195, v35
	v_pk_mov_b32 v[34:35], v[38:39], v[34:35] op_sel:[1,0]
	s_nop 0
	v_pk_mul_f32 v[34:35], v[34:35], v[32:33] op_sel:[0,1] op_sel_hi:[1,0]
	s_nop 0
	v_pk_fma_f32 v[194:195], v[194:195], v[32:33], v[34:35]
	ds_read_b128 v[32:35], v44
	ds_read_b128 v[36:39], v45
	v_pk_add_f32 v[4:5], v[4:5], v[194:195]
	v_and_b32_e32 v195, 0xffff0000, v196
	v_lshlrev_b32_e32 v194, 16, v196
	s_waitcnt lgkmcnt(1)
	v_mov_b32_e32 v41, v33
	s_waitcnt lgkmcnt(0)
	v_pk_mov_b32 v[32:33], v[36:37], v[32:33] op_sel:[1,0]
	v_mov_b32_e32 v40, v36
	v_pk_mul_f32 v[32:33], v[32:33], v[194:195] op_sel:[0,1] op_sel_hi:[1,0]
	v_mov_b32_e32 v196, v38
	v_pk_fma_f32 v[194:195], v[40:41], v[194:195], v[32:33]
	v_pk_mov_b32 v[32:33], v[38:39], v[34:35] op_sel:[1,0]
	v_pk_add_f32 v[4:5], v[4:5], v[194:195]
	v_and_b32_e32 v195, 0xffff0000, v197
	v_lshlrev_b32_e32 v194, 16, v197
	v_mov_b32_e32 v197, v35
	v_pk_mul_f32 v[32:33], v[32:33], v[194:195] op_sel:[0,1] op_sel_hi:[1,0]
	v_and_b32_e32 v37, 0xffff0000, v144
	v_pk_fma_f32 v[194:195], v[196:197], v[194:195], v[32:33]
	v_add_u32_e32 v32, 0x12060, v52
	v_pk_add_f32 v[4:5], v[4:5], v[194:195]
	v_add_u32_e32 v194, 0x11860, v52
	ds_read_b128 v[28:31], v194
	ds_read_b128 v[32:35], v32
	v_lshlrev_b32_e32 v36, 16, v144
	v_add_u32_e32 v40, 0x11870, v52
	v_add_u32_e32 v41, 0x12070, v52
	s_waitcnt lgkmcnt(1)
	v_mov_b32_e32 v39, v29
	s_waitcnt lgkmcnt(0)
	v_pk_mov_b32 v[28:29], v[32:33], v[28:29] op_sel:[1,0]
	v_mov_b32_e32 v38, v32
	v_pk_mul_f32 v[28:29], v[28:29], v[36:37] op_sel:[0,1] op_sel_hi:[1,0]
	v_mov_b32_e32 v144, v34
	v_pk_fma_f32 v[28:29], v[38:39], v[36:37], v[28:29]
	s_nop 0
	v_pk_add_f32 v[4:5], v[4:5], v[28:29]
	v_and_b32_e32 v29, 0xffff0000, v145
	v_lshlrev_b32_e32 v28, 16, v145
	v_mov_b32_e32 v145, v31
	v_pk_mov_b32 v[30:31], v[34:35], v[30:31] op_sel:[1,0]
	s_nop 0
	v_pk_mul_f32 v[30:31], v[30:31], v[28:29] op_sel:[0,1] op_sel_hi:[1,0]
	s_nop 0
	v_pk_fma_f32 v[144:145], v[144:145], v[28:29], v[30:31]
	ds_read_b128 v[28:31], v40
	ds_read_b128 v[32:35], v41
	v_pk_add_f32 v[4:5], v[4:5], v[144:145]
	v_and_b32_e32 v145, 0xffff0000, v146
	v_lshlrev_b32_e32 v144, 16, v146
	s_waitcnt lgkmcnt(1)
	v_mov_b32_e32 v37, v29
	s_waitcnt lgkmcnt(0)
	v_pk_mov_b32 v[28:29], v[32:33], v[28:29] op_sel:[1,0]
	v_mov_b32_e32 v36, v32
	v_pk_mul_f32 v[28:29], v[28:29], v[144:145] op_sel:[0,1] op_sel_hi:[1,0]
	v_mov_b32_e32 v146, v34
	v_pk_fma_f32 v[144:145], v[36:37], v[144:145], v[28:29]
	v_pk_mov_b32 v[28:29], v[34:35], v[30:31] op_sel:[1,0]
	v_pk_add_f32 v[4:5], v[4:5], v[144:145]
	v_and_b32_e32 v145, 0xffff0000, v147
	v_lshlrev_b32_e32 v144, 16, v147
	v_mov_b32_e32 v147, v31
	v_pk_mul_f32 v[28:29], v[28:29], v[144:145] op_sel:[0,1] op_sel_hi:[1,0]
	s_nop 0
	v_pk_fma_f32 v[144:145], v[146:147], v[144:145], v[28:29]
	s_nop 0
	v_pk_add_f32 v[4:5], v[4:5], v[144:145]
	v_mov_b32_e32 v24, v144
	v_mov_b32_e32 v25, v145
	v_mov_b32_e32 v26, v146
	v_mov_b32_e32 v27, v147
	v_add_u32_e32 v52, s5, v8
	v_add_u32_e32 v40, 0x11800, v52
	v_add_u32_e32 v44, 0x12000, v52
	ds_read_b128 v[40:43], v40
	ds_read_b128 v[44:47], v44
	v_add_u32_e32 v53, 0x11810, v52
	v_add_u32_e32 v54, 0x12010, v52
	s_addk_i32 s5, 0x80
	s_waitcnt lgkmcnt(1)
	v_mov_b32_e32 v51, v41
	s_waitcnt lgkmcnt(0)
	v_pk_mov_b32 v[40:41], v[44:45], v[40:41] op_sel:[1,0]
	v_mov_b32_e32 v50, v44
	v_lshl_add_u64 v[6:7], v[6:7], 0, 64
	s_cmpk_lg_i32 s5, 0x200
	s_waitcnt vmcnt(0)
	v_and_b32_e32 v49, 0xffff0000, v218
	v_lshlrev_b32_e32 v48, 16, v218
	v_pk_mul_f32 v[40:41], v[40:41], v[48:49] op_sel:[0,1] op_sel_hi:[1,0]
	v_mov_b32_e32 v218, v46
	v_pk_fma_f32 v[40:41], v[50:51], v[48:49], v[40:41]
	s_nop 0
	v_pk_add_f32 v[4:5], v[4:5], v[40:41]
	v_and_b32_e32 v41, 0xffff0000, v219
	v_lshlrev_b32_e32 v40, 16, v219
	v_mov_b32_e32 v219, v43
	v_pk_mov_b32 v[42:43], v[46:47], v[42:43] op_sel:[1,0]
	s_nop 0
	v_pk_mul_f32 v[42:43], v[42:43], v[40:41] op_sel:[0,1] op_sel_hi:[1,0]
	s_nop 0
	v_pk_fma_f32 v[218:219], v[218:219], v[40:41], v[42:43]
	ds_read_b128 v[40:43], v53
	ds_read_b128 v[44:47], v54
	v_pk_add_f32 v[4:5], v[4:5], v[218:219]
	v_and_b32_e32 v219, 0xffff0000, v220
	v_lshlrev_b32_e32 v218, 16, v220
	s_waitcnt lgkmcnt(1)
	v_mov_b32_e32 v49, v41
	s_waitcnt lgkmcnt(0)
	v_pk_mov_b32 v[40:41], v[44:45], v[40:41] op_sel:[1,0]
	v_mov_b32_e32 v48, v44
	v_pk_mul_f32 v[40:41], v[40:41], v[218:219] op_sel:[0,1] op_sel_hi:[1,0]
	v_mov_b32_e32 v220, v46
	v_pk_fma_f32 v[218:219], v[48:49], v[218:219], v[40:41]
	v_pk_mov_b32 v[40:41], v[46:47], v[42:43] op_sel:[1,0]
	v_pk_add_f32 v[4:5], v[4:5], v[218:219]
	v_and_b32_e32 v219, 0xffff0000, v221
	v_lshlrev_b32_e32 v218, 16, v221
	v_mov_b32_e32 v221, v43
	v_pk_mul_f32 v[40:41], v[40:41], v[218:219] op_sel:[0,1] op_sel_hi:[1,0]
	v_and_b32_e32 v45, 0xffff0000, v214
	v_pk_fma_f32 v[218:219], v[220:221], v[218:219], v[40:41]
	v_add_u32_e32 v40, 0x12020, v52
	v_pk_add_f32 v[4:5], v[4:5], v[218:219]
	v_add_u32_e32 v218, 0x11820, v52
	ds_read_b128 v[36:39], v218
	ds_read_b128 v[40:43], v40
	v_lshlrev_b32_e32 v44, 16, v214
	v_add_u32_e32 v48, 0x11830, v52
	v_add_u32_e32 v49, 0x12030, v52
	s_waitcnt lgkmcnt(1)
	v_mov_b32_e32 v47, v37
	s_waitcnt lgkmcnt(0)
	v_pk_mov_b32 v[36:37], v[40:41], v[36:37] op_sel:[1,0]
	v_mov_b32_e32 v46, v40
	v_pk_mul_f32 v[36:37], v[36:37], v[44:45] op_sel:[0,1] op_sel_hi:[1,0]
	v_mov_b32_e32 v214, v42
	v_pk_fma_f32 v[36:37], v[46:47], v[44:45], v[36:37]
	s_nop 0
	v_pk_add_f32 v[4:5], v[4:5], v[36:37]
	v_and_b32_e32 v37, 0xffff0000, v215
	v_lshlrev_b32_e32 v36, 16, v215
	v_mov_b32_e32 v215, v39
	v_pk_mov_b32 v[38:39], v[42:43], v[38:39] op_sel:[1,0]
	s_nop 0
	v_pk_mul_f32 v[38:39], v[38:39], v[36:37] op_sel:[0,1] op_sel_hi:[1,0]
	s_nop 0
	v_pk_fma_f32 v[214:215], v[214:215], v[36:37], v[38:39]
	ds_read_b128 v[36:39], v48
	ds_read_b128 v[40:43], v49
	v_pk_add_f32 v[4:5], v[4:5], v[214:215]
	v_and_b32_e32 v215, 0xffff0000, v216
	v_lshlrev_b32_e32 v214, 16, v216
	s_waitcnt lgkmcnt(1)
	v_mov_b32_e32 v45, v37
	s_waitcnt lgkmcnt(0)
	v_pk_mov_b32 v[36:37], v[40:41], v[36:37] op_sel:[1,0]
	v_mov_b32_e32 v44, v40
	v_pk_mul_f32 v[36:37], v[36:37], v[214:215] op_sel:[0,1] op_sel_hi:[1,0]
	v_mov_b32_e32 v216, v42
	v_pk_fma_f32 v[214:215], v[44:45], v[214:215], v[36:37]
	v_pk_mov_b32 v[36:37], v[42:43], v[38:39] op_sel:[1,0]
	v_pk_add_f32 v[4:5], v[4:5], v[214:215]
	v_and_b32_e32 v215, 0xffff0000, v217
	v_lshlrev_b32_e32 v214, 16, v217
	v_mov_b32_e32 v217, v39
	v_pk_mul_f32 v[36:37], v[36:37], v[214:215] op_sel:[0,1] op_sel_hi:[1,0]
	v_and_b32_e32 v41, 0xffff0000, v210
	v_pk_fma_f32 v[214:215], v[216:217], v[214:215], v[36:37]
	v_add_u32_e32 v36, 0x12040, v52
	v_pk_add_f32 v[4:5], v[4:5], v[214:215]
	v_add_u32_e32 v214, 0x11840, v52
	ds_read_b128 v[32:35], v214
	ds_read_b128 v[36:39], v36
	v_lshlrev_b32_e32 v40, 16, v210
	v_add_u32_e32 v44, 0x11850, v52
	v_add_u32_e32 v45, 0x12050, v52
	s_waitcnt lgkmcnt(1)
	v_mov_b32_e32 v43, v33
	s_waitcnt lgkmcnt(0)
	v_pk_mov_b32 v[32:33], v[36:37], v[32:33] op_sel:[1,0]
	v_mov_b32_e32 v42, v36
	v_pk_mul_f32 v[32:33], v[32:33], v[40:41] op_sel:[0,1] op_sel_hi:[1,0]
	v_mov_b32_e32 v210, v38
	v_pk_fma_f32 v[32:33], v[42:43], v[40:41], v[32:33]
	s_nop 0
	v_pk_add_f32 v[4:5], v[4:5], v[32:33]
	v_and_b32_e32 v33, 0xffff0000, v211
	v_lshlrev_b32_e32 v32, 16, v211
	v_mov_b32_e32 v211, v35
	v_pk_mov_b32 v[34:35], v[38:39], v[34:35] op_sel:[1,0]
	s_nop 0
	v_pk_mul_f32 v[34:35], v[34:35], v[32:33] op_sel:[0,1] op_sel_hi:[1,0]
	s_nop 0
	v_pk_fma_f32 v[210:211], v[210:211], v[32:33], v[34:35]
	ds_read_b128 v[32:35], v44
	ds_read_b128 v[36:39], v45
	v_pk_add_f32 v[4:5], v[4:5], v[210:211]
	v_and_b32_e32 v211, 0xffff0000, v212
	v_lshlrev_b32_e32 v210, 16, v212
	s_waitcnt lgkmcnt(1)
	v_mov_b32_e32 v41, v33
	s_waitcnt lgkmcnt(0)
	v_pk_mov_b32 v[32:33], v[36:37], v[32:33] op_sel:[1,0]
	v_mov_b32_e32 v40, v36
	v_pk_mul_f32 v[32:33], v[32:33], v[210:211] op_sel:[0,1] op_sel_hi:[1,0]
	v_mov_b32_e32 v212, v38
	v_pk_fma_f32 v[210:211], v[40:41], v[210:211], v[32:33]
	v_pk_mov_b32 v[32:33], v[38:39], v[34:35] op_sel:[1,0]
	v_pk_add_f32 v[4:5], v[4:5], v[210:211]
	v_and_b32_e32 v211, 0xffff0000, v213
	v_lshlrev_b32_e32 v210, 16, v213
	v_mov_b32_e32 v213, v35
	v_pk_mul_f32 v[32:33], v[32:33], v[210:211] op_sel:[0,1] op_sel_hi:[1,0]
	v_and_b32_e32 v37, 0xffff0000, v206
	v_pk_fma_f32 v[210:211], v[212:213], v[210:211], v[32:33]
	v_add_u32_e32 v32, 0x12060, v52
	v_pk_add_f32 v[4:5], v[4:5], v[210:211]
	v_add_u32_e32 v210, 0x11860, v52
	ds_read_b128 v[28:31], v210
	ds_read_b128 v[32:35], v32
	v_lshlrev_b32_e32 v36, 16, v206
	v_add_u32_e32 v40, 0x11870, v52
	v_add_u32_e32 v41, 0x12070, v52
	s_waitcnt lgkmcnt(1)
	v_mov_b32_e32 v39, v29
	s_waitcnt lgkmcnt(0)
	v_pk_mov_b32 v[28:29], v[32:33], v[28:29] op_sel:[1,0]
	v_mov_b32_e32 v38, v32
	v_pk_mul_f32 v[28:29], v[28:29], v[36:37] op_sel:[0,1] op_sel_hi:[1,0]
	v_mov_b32_e32 v206, v34
	v_pk_fma_f32 v[28:29], v[38:39], v[36:37], v[28:29]
	s_nop 0
	v_pk_add_f32 v[4:5], v[4:5], v[28:29]
	v_and_b32_e32 v29, 0xffff0000, v207
	v_lshlrev_b32_e32 v28, 16, v207
	v_mov_b32_e32 v207, v31
	v_pk_mov_b32 v[30:31], v[34:35], v[30:31] op_sel:[1,0]
	s_nop 0
	v_pk_mul_f32 v[30:31], v[30:31], v[28:29] op_sel:[0,1] op_sel_hi:[1,0]
	s_nop 0
	v_pk_fma_f32 v[206:207], v[206:207], v[28:29], v[30:31]
	ds_read_b128 v[28:31], v40
	ds_read_b128 v[32:35], v41
	v_pk_add_f32 v[4:5], v[4:5], v[206:207]
	v_and_b32_e32 v207, 0xffff0000, v208
	v_lshlrev_b32_e32 v206, 16, v208
	s_waitcnt lgkmcnt(1)
	v_mov_b32_e32 v37, v29
	s_waitcnt lgkmcnt(0)
	v_pk_mov_b32 v[28:29], v[32:33], v[28:29] op_sel:[1,0]
	v_mov_b32_e32 v36, v32
	v_pk_mul_f32 v[28:29], v[28:29], v[206:207] op_sel:[0,1] op_sel_hi:[1,0]
	v_mov_b32_e32 v208, v34
	v_pk_fma_f32 v[206:207], v[36:37], v[206:207], v[28:29]
	v_pk_mov_b32 v[28:29], v[34:35], v[30:31] op_sel:[1,0]
	v_pk_add_f32 v[4:5], v[4:5], v[206:207]
	v_and_b32_e32 v207, 0xffff0000, v209
	v_lshlrev_b32_e32 v206, 16, v209
	v_mov_b32_e32 v209, v31
	v_pk_mul_f32 v[28:29], v[28:29], v[206:207] op_sel:[0,1] op_sel_hi:[1,0]
	s_nop 0
	v_pk_fma_f32 v[206:207], v[208:209], v[206:207], v[28:29]
	s_nop 0
	v_pk_add_f32 v[4:5], v[4:5], v[206:207]
	v_mov_b32_e32 v24, v206
	v_mov_b32_e32 v25, v207
	v_mov_b32_e32 v26, v208
	v_mov_b32_e32 v27, v209
	s_cmp_eq_u32 s52, 0
	s_cselect_b64 s[42:43], -1, 0
	s_cmp_gt_u32 s52, 1
	s_cselect_b64 s[46:47], -1, 0
	s_cmp_gt_u32 s52, 2
	v_cndmask_b32_e64 v6, v23, v188, s[42:43]
	v_cndmask_b32_e64 v7, v188, v22, s[46:47]
	s_cselect_b64 vcc, -1, 0
	v_cndmask_b32_e32 v8, v188, v21, vcc
	s_cmp_gt_u32 s52, 3
	v_cmp_gt_f32_e64 s[50:51], v7, v6
	s_cselect_b64 s[38:39], -1, 0
	s_cmp_gt_u32 s52, 4
	v_cndmask_b32_e64 v21, 0, 1, s[50:51]
	v_cmp_gt_f32_e64 s[50:51], v8, v6
	v_cndmask_b32_e64 v20, v188, v20, s[38:39]
	s_cselect_b64 s[40:41], -1, 0
	v_addc_co_u32_e64 v21, s[50:51], 0, v21, s[50:51]
	v_cndmask_b32_e64 v19, v188, v19, s[40:41]
	s_cmp_gt_u32 s52, 5
	v_cmp_gt_f32_e64 s[50:51], v20, v6
	s_cselect_b64 s[44:45], -1, 0
	s_cmp_eq_u32 s52, 7
	v_cndmask_b32_e64 v22, 0, 1, s[50:51]
	v_cmp_gt_f32_e64 s[50:51], v19, v6
	v_cndmask_b32_e64 v18, v188, v18, s[44:45]
	s_cselect_b64 s[48:49], -1, 0
	v_addc_co_u32_e64 v21, s[50:51], v21, v22, s[50:51]
	v_cndmask_b32_e64 v17, v188, v17, s[48:49]
	v_cmp_gt_f32_e64 s[50:51], v18, v6
	s_lshl_b32 s5, -1, s52
	v_lshlrev_b32_e32 v191, 2, v12
	v_cndmask_b32_e64 v22, 0, 1, s[50:51]
	v_cmp_gt_f32_e64 s[50:51], v17, v6
	s_lshl_b32 s17, s52, 2
	s_mov_b32 s85, 0
	v_addc_co_u32_e64 v21, s[50:51], v21, v22, s[50:51]
	v_cmp_gt_u32_e64 s[50:51], 3, v21
	s_or_b32 s16, s4, 31
	v_add_u32_e32 v179, 14, v149
	v_cndmask_b32_e64 v21, 0, 1, s[50:51]
	v_cmp_ge_f32_e64 s[50:51], v6, v7
	v_add_u32_e32 v178, 13, v149
	v_mov_b32_e32 v177, 0
	v_cndmask_b32_e64 v22, 0, 1, s[50:51]
	v_cmp_gt_f32_e64 s[50:51], v8, v7
	v_mov_b32_e32 v181, 0xf149f2ca
	s_nop 0
	v_addc_co_u32_e64 v22, s[50:51], 0, v22, s[50:51]
	v_cmp_gt_f32_e64 s[50:51], v20, v7
	s_nop 1
	v_cndmask_b32_e64 v23, 0, 1, s[50:51]
	v_cmp_gt_f32_e64 s[50:51], v19, v7
	s_nop 1
	v_addc_co_u32_e64 v22, s[50:51], v22, v23, s[50:51]
	v_cmp_gt_f32_e64 s[50:51], v18, v7
	s_nop 1
	v_cndmask_b32_e64 v23, 0, 1, s[50:51]
	v_cmp_gt_f32_e64 s[50:51], v17, v7
	s_nop 1
	v_addc_co_u32_e64 v22, s[50:51], v22, v23, s[50:51]
	v_cmp_lt_u32_e64 s[50:51], 2, v22
	s_nop 1
	v_cndmask_b32_e64 v22, 2, 0, s[50:51]
	v_cmp_ge_f32_e64 s[50:51], v7, v8
	v_or_b32_e32 v21, v22, v21
	s_nop 0
	v_cndmask_b32_e64 v22, 0, 1, s[50:51]
	v_cmp_ge_f32_e64 s[50:51], v6, v8
	s_nop 1
	v_addc_co_u32_e64 v22, s[50:51], 0, v22, s[50:51]
	v_cmp_gt_f32_e64 s[50:51], v20, v8
	s_nop 1
	v_cndmask_b32_e64 v23, 0, 1, s[50:51]
	v_cmp_gt_f32_e64 s[50:51], v19, v8
	s_nop 1
	v_addc_co_u32_e64 v22, s[50:51], v22, v23, s[50:51]
	v_cmp_gt_f32_e64 s[50:51], v18, v8
	s_nop 1
	v_cndmask_b32_e64 v23, 0, 1, s[50:51]
	v_cmp_gt_f32_e64 s[50:51], v17, v8
	s_nop 1
	v_addc_co_u32_e64 v22, s[50:51], v22, v23, s[50:51]
	v_cmp_gt_u32_e64 s[50:51], 3, v22
	s_nop 1
	v_cndmask_b32_e64 v22, 0, 4, s[50:51]
	v_cmp_ge_f32_e64 s[50:51], v7, v20
	s_nop 1
	v_cndmask_b32_e64 v23, 0, 1, s[50:51]
	v_cmp_ge_f32_e64 s[50:51], v6, v20
	s_nop 1
	v_addc_co_u32_e64 v23, s[50:51], 0, v23, s[50:51]
	v_cmp_ge_f32_e64 s[50:51], v8, v20
	s_nop 1
	v_cndmask_b32_e64 v24, 0, 1, s[50:51]
	v_cmp_gt_f32_e64 s[50:51], v19, v20
	s_nop 1
	v_addc_co_u32_e64 v23, s[50:51], v23, v24, s[50:51]
	v_cmp_gt_f32_e64 s[50:51], v18, v20
	s_nop 1
	v_cndmask_b32_e64 v24, 0, 1, s[50:51]
	v_cmp_gt_f32_e64 s[50:51], v17, v20
	s_nop 1
	v_addc_co_u32_e64 v23, s[50:51], v23, v24, s[50:51]
	v_cmp_gt_u32_e64 s[50:51], 3, v23
	s_nop 1
	v_cndmask_b32_e64 v23, 0, 8, s[50:51]
	v_cmp_ge_f32_e64 s[50:51], v7, v19
	v_or3_b32 v21, v21, v22, v23
	s_nop 0
	v_cndmask_b32_e64 v22, 0, 1, s[50:51]
	v_cmp_ge_f32_e64 s[50:51], v6, v19
	s_nop 1
	v_addc_co_u32_e64 v22, s[50:51], 0, v22, s[50:51]
	v_cmp_ge_f32_e64 s[50:51], v8, v19
	s_nop 1
	v_cndmask_b32_e64 v23, 0, 1, s[50:51]
	v_cmp_ge_f32_e64 s[50:51], v20, v19
	s_nop 1
	v_addc_co_u32_e64 v22, s[50:51], v22, v23, s[50:51]
	v_cmp_gt_f32_e64 s[50:51], v18, v19
	s_nop 1
	v_cndmask_b32_e64 v23, 0, 1, s[50:51]
	v_cmp_gt_f32_e64 s[50:51], v17, v19
	s_nop 1
	v_addc_co_u32_e64 v22, s[50:51], v22, v23, s[50:51]
	v_cmp_gt_u32_e64 s[50:51], 3, v22
	s_nop 1
	v_cndmask_b32_e64 v22, 0, 16, s[50:51]
	v_cmp_ge_f32_e64 s[50:51], v7, v18
	s_nop 1
	v_cndmask_b32_e64 v23, 0, 1, s[50:51]
	v_cmp_ge_f32_e64 s[50:51], v6, v18
	s_nop 1
	v_addc_co_u32_e64 v23, s[50:51], 0, v23, s[50:51]
	v_cmp_ge_f32_e64 s[50:51], v8, v18
	s_nop 1
	v_cndmask_b32_e64 v24, 0, 1, s[50:51]
	v_cmp_ge_f32_e64 s[50:51], v20, v18
	s_nop 1
	v_addc_co_u32_e64 v23, s[50:51], v23, v24, s[50:51]
	v_cmp_ge_f32_e64 s[50:51], v19, v18
	s_nop 1
	v_cndmask_b32_e64 v24, 0, 1, s[50:51]
	v_cmp_gt_f32_e64 s[50:51], v17, v18
	s_nop 1
	v_addc_co_u32_e64 v23, s[50:51], v23, v24, s[50:51]
	v_cmp_gt_u32_e64 s[50:51], 3, v23
	s_nop 1
	v_cndmask_b32_e64 v23, 0, 32, s[50:51]
	v_cmp_ge_f32_e64 s[50:51], v7, v17
	v_or3_b32 v21, v21, v22, v23
	s_nop 0
	v_cndmask_b32_e64 v7, 0, 1, s[50:51]
	v_cmp_ge_f32_e64 s[50:51], v6, v17
	s_nop 1
	v_addc_co_u32_e64 v6, s[50:51], 0, v7, s[50:51]
	v_cmp_ge_f32_e64 s[50:51], v8, v17
	ds_bpermute_b32 v8, v14, v5
	s_waitcnt lgkmcnt(0)
	v_cndmask_b32_e64 v23, v188, v8, s[46:47]
	v_cndmask_b32_e64 v7, 0, 1, s[50:51]
	v_cmp_ge_f32_e64 s[50:51], v20, v17
	ds_bpermute_b32 v8, v14, v4
	s_waitcnt lgkmcnt(0)
	v_cndmask_b32_e64 v27, v188, v8, s[44:45]
	v_addc_co_u32_e64 v6, s[50:51], v6, v7, s[50:51]
	v_cmp_ge_f32_e64 s[50:51], v19, v17
	v_lshlrev_b32_e32 v8, 4, v12
	s_nop 0
	v_cndmask_b32_e64 v7, 0, 1, s[50:51]
	v_cmp_ge_f32_e64 s[50:51], v18, v17
	s_nop 1
	v_addc_co_u32_e64 v6, s[50:51], v6, v7, s[50:51]
	ds_bpermute_b32 v7, v13, v5
	v_cmp_gt_u32_e64 s[50:51], 3, v6
	s_waitcnt lgkmcnt(0)
	v_cndmask_b32_e64 v22, v7, v188, s[42:43]
	v_cndmask_b32_e64 v6, 0, 64, s[50:51]
	v_or_b32_e32 v24, v21, v6
	v_bitop3_b32 v190, v21, s5, v6 bitop3:0x32
	ds_bpermute_b32 v6, v15, v5
	ds_bpermute_b32 v7, v13, v4
	ds_bpermute_b32 v4, v15, v4
	ds_bpermute_b32 v5, v16, v5
	s_waitcnt lgkmcnt(3)
	v_cndmask_b32_e32 v13, v188, v6, vcc
	v_cmp_gt_f32_e32 vcc, v23, v22
	s_waitcnt lgkmcnt(1)
	v_cndmask_b32_e64 v28, v188, v4, s[48:49]
	s_waitcnt lgkmcnt(0)
	v_cndmask_b32_e64 v25, v188, v5, s[38:39]
	v_cndmask_b32_e64 v4, 0, 1, vcc
	v_cmp_gt_f32_e32 vcc, v13, v22
	v_cndmask_b32_e64 v26, v188, v7, s[40:41]
	s_nop 0
	v_addc_co_u32_e32 v4, vcc, 0, v4, vcc
	v_cmp_gt_f32_e32 vcc, v25, v22
	s_nop 1
	v_cndmask_b32_e64 v5, 0, 1, vcc
	v_cmp_gt_f32_e32 vcc, v26, v22
	s_nop 1
	v_addc_co_u32_e32 v4, vcc, v4, v5, vcc
	v_cmp_gt_f32_e32 vcc, v27, v22
	s_nop 1
	v_cndmask_b32_e64 v5, 0, 1, vcc
	v_cmp_gt_f32_e32 vcc, v28, v22
	s_nop 1
	v_addc_co_u32_e32 v4, vcc, v4, v5, vcc
	v_cmp_gt_u32_e32 vcc, 3, v4
	s_nop 1
	v_cndmask_b32_e64 v4, 0, 1, vcc
	v_cmp_ge_f32_e32 vcc, v22, v23
	s_nop 1
	v_cndmask_b32_e64 v5, 0, 1, vcc
	v_cmp_gt_f32_e32 vcc, v13, v23
	s_nop 1
	v_addc_co_u32_e32 v5, vcc, 0, v5, vcc
	v_cmp_gt_f32_e32 vcc, v25, v23
	s_nop 1
	v_cndmask_b32_e64 v6, 0, 1, vcc
	v_cmp_gt_f32_e32 vcc, v26, v23
	s_nop 1
	v_addc_co_u32_e32 v5, vcc, v5, v6, vcc
	v_cmp_gt_f32_e32 vcc, v27, v23
	s_nop 1
	v_cndmask_b32_e64 v6, 0, 1, vcc
	v_cmp_gt_f32_e32 vcc, v28, v23
	s_nop 1
	v_addc_co_u32_e32 v5, vcc, v5, v6, vcc
	v_cmp_lt_u32_e32 vcc, 2, v5
	v_mov_b32_e32 v6, v170
	s_nop 0
	v_cndmask_b32_e64 v5, 2, 0, vcc
	v_cmp_ge_f32_e32 vcc, v23, v13
	v_or_b32_e32 v29, v5, v4
	s_nop 0
	v_cndmask_b32_e64 v4, 0, 1, vcc
	v_cmp_ge_f32_e32 vcc, v22, v13
	s_nop 1
	v_addc_co_u32_e32 v4, vcc, 0, v4, vcc
	v_cmp_gt_f32_e32 vcc, v25, v13
	s_nop 1
	v_cndmask_b32_e64 v5, 0, 1, vcc
	v_cmp_gt_f32_e32 vcc, v26, v13
	s_nop 1
	v_addc_co_u32_e32 v4, vcc, v4, v5, vcc
	v_cmp_gt_f32_e32 vcc, v27, v13
	s_nop 1
	v_cndmask_b32_e64 v5, 0, 1, vcc
	v_cmp_gt_f32_e32 vcc, v28, v13
	s_nop 1
	v_addc_co_u32_e32 v4, vcc, v4, v5, vcc
	v_cmp_gt_u32_e32 vcc, 3, v4
	s_nop 1
	v_cndmask_b32_e64 v30, 0, 4, vcc
	v_cmp_ge_f32_e32 vcc, v23, v25
	s_nop 1
	v_cndmask_b32_e64 v4, 0, 1, vcc
	v_cmp_ge_f32_e32 vcc, v22, v25
	s_nop 1
	v_addc_co_u32_e32 v4, vcc, 0, v4, vcc
	v_cmp_ge_f32_e32 vcc, v13, v25
	s_nop 1
	v_cndmask_b32_e64 v5, 0, 1, vcc
	v_cmp_gt_f32_e32 vcc, v26, v25
	s_nop 1
	v_addc_co_u32_e32 v31, vcc, v4, v5, vcc
	v_lshl_add_u64 v[4:5], s[22:23], 0, v[8:9]
	v_lshl_add_u64 v[0:1], v[4:5], 0, v[0:1]
	global_load_dwordx4 v[92:95], v[0:1], off
	global_load_dwordx4 v[84:87], v[0:1], off offset:64
	global_load_dwordx4 v[76:79], v[0:1], off offset:128
	global_load_dwordx4 v[68:71], v[0:1], off offset:192
	v_lshl_add_u64 v[0:1], v[4:5], 0, v[2:3]
	global_load_dwordx4 v[96:99], v[0:1], off
	global_load_dwordx4 v[88:91], v[0:1], off offset:64
	global_load_dwordx4 v[80:83], v[0:1], off offset:128
	global_load_dwordx4 v[72:75], v[0:1], off offset:192
	v_cmp_gt_f32_e32 vcc, v27, v25
	v_lshlrev_b32_e32 v0, 4, v6
	v_and_b32_e32 v8, 0xf0, v0
	v_lshrrev_b32_e32 v0, 4, v6
	v_lshl_add_u64 v[4:5], s[24:25], 0, v[8:9]
	v_add_u32_e32 v14, s9, v0
	v_mad_u64_u32 v[0:1], s[6:7], v14, s65, v[4:5]
	v_add_u32_e32 v6, 0x200, v6
	global_load_dwordx4 v[0:3], v[0:1], off
	v_lshrrev_b32_e32 v6, 4, v6
	v_add_u32_e32 v20, s9, v6
	v_mad_u64_u32 v[4:5], s[6:7], v20, s65, v[4:5]
	v_lshl_add_u64 v[18:19], s[26:27], 0, v[8:9]
	global_load_dwordx4 v[4:7], v[4:5], off
	v_mad_u64_u32 v[14:15], s[6:7], v14, s65, v[18:19]
	global_load_dwordx4 v[14:17], v[14:15], off
	v_mad_u64_u32 v[18:19], s[6:7], v20, s65, v[18:19]
	global_load_dwordx4 v[18:21], v[18:19], off
	v_cndmask_b32_e64 v32, 0, 1, vcc
	v_cmp_gt_f32_e32 vcc, v28, v25
	s_nop 1
	v_addc_co_u32_e32 v8, vcc, v31, v32, vcc
	v_cmp_gt_u32_e32 vcc, 3, v8
	s_nop 1
	v_cndmask_b32_e64 v8, 0, 8, vcc
	v_cmp_ge_f32_e32 vcc, v23, v26
	v_or3_b32 v8, v29, v30, v8
	s_nop 0
	v_cndmask_b32_e64 v29, 0, 1, vcc
	v_cmp_ge_f32_e32 vcc, v22, v26
	s_nop 1
	v_addc_co_u32_e32 v29, vcc, 0, v29, vcc
	v_cmp_ge_f32_e32 vcc, v13, v26
	s_nop 1
	v_cndmask_b32_e64 v30, 0, 1, vcc
	v_cmp_ge_f32_e32 vcc, v25, v26
	s_nop 1
	v_addc_co_u32_e32 v29, vcc, v29, v30, vcc
	v_cmp_gt_f32_e32 vcc, v27, v26
	s_nop 1
	v_cndmask_b32_e64 v30, 0, 1, vcc
	v_cmp_gt_f32_e32 vcc, v28, v26
	s_nop 1
	v_addc_co_u32_e32 v29, vcc, v29, v30, vcc
	v_cmp_gt_u32_e32 vcc, 3, v29
	s_nop 1
	v_cndmask_b32_e64 v29, 0, 16, vcc
	v_cmp_ge_f32_e32 vcc, v23, v27
	s_nop 1
	v_cndmask_b32_e64 v30, 0, 1, vcc
	v_cmp_ge_f32_e32 vcc, v22, v27
	s_nop 1
	v_addc_co_u32_e32 v30, vcc, 0, v30, vcc
	v_cmp_ge_f32_e32 vcc, v13, v27
	s_nop 1
	v_cndmask_b32_e64 v31, 0, 1, vcc
	v_cmp_ge_f32_e32 vcc, v25, v27
	s_nop 1
	v_addc_co_u32_e32 v30, vcc, v30, v31, vcc
	v_cmp_ge_f32_e32 vcc, v26, v27
	s_nop 1
	v_cndmask_b32_e64 v31, 0, 1, vcc
	v_cmp_gt_f32_e32 vcc, v28, v27
	s_nop 1
	v_addc_co_u32_e32 v30, vcc, v30, v31, vcc
	v_cmp_gt_u32_e32 vcc, 3, v30
	s_nop 1
	v_cndmask_b32_e64 v30, 0, 32, vcc
	v_cmp_ge_f32_e32 vcc, v23, v28
	v_or3_b32 v8, v8, v29, v30
	s_nop 0
	v_cndmask_b32_e64 v23, 0, 1, vcc
	v_cmp_ge_f32_e32 vcc, v22, v28
	s_nop 1
	v_addc_co_u32_e32 v22, vcc, 0, v23, vcc
	v_cmp_ge_f32_e32 vcc, v13, v28
	s_nop 1
	v_cndmask_b32_e64 v13, 0, 1, vcc
	v_cmp_ge_f32_e32 vcc, v25, v28
	s_nop 1
	v_addc_co_u32_e32 v13, vcc, v22, v13, vcc
	v_cmp_ge_f32_e32 vcc, v26, v28
	s_nop 1
	v_cndmask_b32_e64 v22, 0, 1, vcc
	v_cmp_ge_f32_e32 vcc, v27, v28
	s_nop 1
	v_addc_co_u32_e32 v13, vcc, v13, v22, vcc
	v_cmp_gt_u32_e32 vcc, 3, v13
	s_nop 1
	v_cndmask_b32_e64 v13, 0, 64, vcc
	v_or_b32_e32 v25, v8, v13
	v_bitop3_b32 v180, v8, s5, v13 bitop3:0x32
	v_mov_b32_e32 v13, v170
	v_bitop3_b32 v193, v25, v24, s5 bitop3:0x54
	v_lshlrev_b32_e32 v8, 4, v13
	v_and_b32_e32 v8, 0xf0, v8
	v_add_u32_e32 v8, 0, v8
	v_lshrrev_b32_e32 v26, 4, v13
	v_and_b32_e32 v248, 0xf0, v13
	v_xor_b32_e32 v248, v248, v8
	v_mov_b32_e32 v249, 0
	v_mad_u64_u32 v[22:23], s[6:7], v26, s33, v[248:249]
	s_waitcnt vmcnt(3)
	ds_write_b128 v22, v[0:3]
	v_add_u32_e32 v0, 0x200, v13
	v_lshrrev_b32_e32 v2, 4, v0
	v_mad_u64_u32 v[0:1], s[6:7], v2, s33, v[248:249]
	s_waitcnt vmcnt(2)
	ds_write_b128 v0, v[4:7]
	v_and_b32_e32 v22, 7, v26
	v_lshlrev_b32_e32 v22, 5, v22
	v_xor_b32_e32 v8, v8, v22
	v_mad_u64_u32 v[0:1], s[6:7], v26, s33, v[8:9]
	s_waitcnt vmcnt(1)
	ds_write_b128 v0, v[14:17] offset:34816
	v_mad_u64_u32 v[0:1], s[6:7], v2, s33, v[8:9]
	s_waitcnt vmcnt(0)
	ds_write_b128 v0, v[18:21] offset:34816
	v_lshlrev_b32_e32 v0, 8, v11
	v_and_b32_e32 v1, 48, v10
	v_lshlrev_b32_e32 v248, 4, v11
	v_xor_b32_e32 v1, v1, v248
	v_add3_u32 v192, 0, v0, v1
	v_lshrrev_b32_e32 v0, 2, v11
	v_or_b32_e32 v0, v191, v0
	v_lshlrev_b32_e32 v1, 3, v10
	v_and_b32_e32 v248, 7, v0
	v_lshlrev_b32_e32 v248, 5, v248
	v_lshl_or_b32 v0, v0, 8, v248
	v_and_b32_e32 v1, 24, v1
	v_add3_u32 v176, 0, v0, v1
	v_and_b32_e32 v1, 64, v184
	v_xor_b32_e32 v0, 16, v184
	v_add_u32_e32 v1, 64, v1
	v_cmp_lt_i32_e32 vcc, v0, v1
	v_mov_b32_e32 v8, v9
	v_mov_b32_e32 v10, v9
	v_cndmask_b32_e32 v0, v184, v0, vcc
	v_lshlrev_b32_e32 v175, 2, v0
	v_xor_b32_e32 v0, 32, v184
	v_cmp_lt_i32_e32 vcc, v0, v1
	v_mov_b32_e32 v11, v9
	v_mov_b64_e32 v[18:19], v[10:11]
	v_cndmask_b32_e32 v0, v184, v0, vcc
	v_lshlrev_b32_e32 v174, 2, v0
	v_mov_b64_e32 v[0:1], v[8:9]
	v_mov_b64_e32 v[26:27], v[10:11]
	v_mov_b64_e32 v[34:35], v[10:11]
	v_mov_b64_e32 v[14:15], v[10:11]
	v_mov_b64_e32 v[4:5], v[8:9]
	v_mov_b64_e32 v[22:23], v[10:11]
	v_mov_b64_e32 v[30:31], v[10:11]
	v_mov_b64_e32 v[38:39], v[10:11]
	v_mov_b64_e32 v[42:43], v[10:11]
	v_mov_b64_e32 v[46:47], v[10:11]
	v_mov_b64_e32 v[50:51], v[10:11]
	v_mov_b64_e32 v[54:55], v[10:11]
	v_mov_b64_e32 v[58:59], v[10:11]
	v_mov_b64_e32 v[62:63], v[10:11]
	v_mov_b64_e32 v[66:67], v[10:11]
	s_or_b32 s6, s17, 2
	v_mov_b64_e32 v[2:3], v[10:11]
	v_mov_b64_e32 v[16:17], v[8:9]
	v_mov_b64_e32 v[24:25], v[8:9]
	v_mov_b64_e32 v[32:33], v[8:9]
	v_mov_b64_e32 v[12:13], v[8:9]
	v_mov_b64_e32 v[6:7], v[10:11]
	v_mov_b64_e32 v[20:21], v[8:9]
	v_mov_b64_e32 v[28:29], v[8:9]
	v_mov_b64_e32 v[36:37], v[8:9]
	v_mov_b64_e32 v[40:41], v[8:9]
	v_mov_b64_e32 v[44:45], v[8:9]
	v_mov_b64_e32 v[48:49], v[8:9]
	v_mov_b64_e32 v[52:53], v[8:9]
	v_mov_b64_e32 v[56:57], v[8:9]
	v_mov_b64_e32 v[60:61], v[8:9]
	v_mov_b64_e32 v[64:65], v[8:9]
	v_mov_b32_e32 v11, 0xf149f2ca
	v_mov_b32_e32 v10, 0
	s_mov_b32 s7, 0
	v_lshrrev_b32_e32 v108, 4, v170
	v_and_b32_e32 v109, 15, v170
	v_and_b32_e32 v110, 15, v108
	v_xor_b32_e32 v110, v109, v110
	v_and_b32_e32 v111, 7, v108
	v_lshlrev_b32_e32 v111, 1, v111
	v_xor_b32_e32 v109, v109, v111
	v_mul_u32_u24_e32 v111, 0x3000, v108
	v_lshl_or_b32 v108, v110, 4, v111
	v_lshl_or_b32 v109, v109, 4, v111
	s_waitcnt lgkmcnt(0)
	s_barrier
